# GEMM K-loops (P2/P7/P8/P9): loop-edge rotation - counter/pointer increments and compare issue inside the last MFMA block; only the branch follows the barrier
# speedup vs baseline: 1.0022x; 1.0022x over previous
; #define PG8_STAGE(bufoff, gbase, voff) do { _Pragma("unroll") for (int _i = 0; _i < 2; ++_i) \
;         __builtin_amdgcn_global_load_lds((const unsigned*)((const char*)(gbase) + (voff)[_i]), (PG8_LAS unsigned*)(lds + (bufoff) + ldsw + _i * 8192), 16, 0, 0); } while (0)
; #define PG8_LDA(dst, b, h) do { _Pragma("unroll") for (int m = 0; m < 4; ++m) _Pragma("unroll") for (int k = 0; k < 2; ++k) dst[m][k] = *(const PG8_LAS bf16x8*)(lds + PG8_SA(b, h) + aoff + m * 2048 + k * 1024); } while (0)
; #define PG8_LDB(dst, b, h) do { _Pragma("unroll") for (int n = 0; n < 2; ++n) _Pragma("unroll") for (int k = 0; k < 2; ++k) dst[n][k] = *(const PG8_LAS bf16x8*)(lds + PG8_SB(b, h) + boff + n * 2048 + k * 1024); } while (0)
; #define PG8_MMA(ai, bj, At, Bt) do { __builtin_amdgcn_s_setprio(1); _Pragma("unroll") for (int m = 0; m < 4; ++m) _Pragma("unroll") for (int n = 0; n < 2; ++n) _Pragma("unroll") for (int k = 0; k < 2; ++k) \
;         acc[ai][bj][m][n] = __builtin_amdgcn_mfma_f32_16x16x32_bf16(Bt[n][k], At[m][k], acc[ai][bj][m][n], 0, 0, 0); __builtin_amdgcn_s_setprio(0); } while (0)
; #define PG8_WAIT_V(n) asm volatile("s_waitcnt vmcnt(" #n ")" ::: "memory")
; #define PG8_WAIT_L(n) asm volatile("s_waitcnt lgkmcnt(" #n ")" ::: "memory")
; #define PG8_BAR __builtin_amdgcn_s_barrier()
; #define PG8_SCHED __builtin_amdgcn_sched_barrier(0)
; template <class Epi, class Sched, bool ALIGN_EPI = false, bool SP2 = false>
; __device__ __forceinline__ void gemm_phase(PG8_LAS unsigned char* lds, const Gemm g, const Sched& S, const Epi& E) {
;     ...
;             PG8_LDB(B0, 0, 0); PG8_LDB(B1, 0, 1); PG8_SCHED; PG8_LDA(At, 0, 0); PG8_STAGE(PG8_SA(1, 1), a1 + hstep, voffA);
;             PG8_WAIT_V(8); PG8_WAIT_L(0); PG8_BAR; PG8_MMA(0, 0, At, B0); PG8_MMA(0, 1, At, B1); PG8_BAR; PG8_SCHED;
;             PG8_LDA(At, 0, 1); PG8_STAGE(PG8_SB(0, 0), b2, voffB); PG8_STAGE(PG8_SB(0, 1), b2 + hstep, voffB); PG8_STAGE(PG8_SA(0, 0), a2, voffA);
;             PG8_WAIT_V(8); PG8_WAIT_L(0); PG8_BAR; PG8_MMA(1, 0, At, B0); PG8_MMA(1, 1, At, B1); PG8_BAR; PG8_SCHED;
.LBB0_270:
	ds_read_b128 v[146:149], v152
	ds_read_b128 v[156:159], v152 offset:1024
	ds_read_b128 v[160:163], v152 offset:2048
	ds_read_b128 v[164:167], v152 offset:3072
	ds_read_b128 v[168:171], v153
	ds_read_b128 v[172:175], v153 offset:1024
	ds_read_b128 v[176:179], v153 offset:2048
	ds_read_b128 v[180:183], v153 offset:3072
	s_add_u32 s3, s88, 0xfffc0080
	s_addc_u32 s90, s89, -1
	s_cmp_eq_u32 s96, 12
	s_cselect_b32 s93, s0, s90
	s_cselect_b32 s92, s1, s3
	s_cselect_b32 s91, s7, s87
	s_cselect_b32 s90, s69, s81
	v_lshl_add_u64 v[216:217], s[88:89], 0, v[138:139]
	s_add_i32 m0, s13, 0xc000
	ds_read_b128 v[184:187], v154
	ds_read_b128 v[188:191], v154 offset:1024
	ds_read_b128 v[192:195], v154 offset:2048
	ds_read_b128 v[196:199], v154 offset:3072
	ds_read_b128 v[200:203], v154 offset:4096
	ds_read_b128 v[204:207], v154 offset:5120
	ds_read_b128 v[208:211], v154 offset:6144
	ds_read_b128 v[212:215], v154 offset:7168
	global_load_lds_dwordx4 v[216:217], off
	v_lshl_add_u64 v[216:217], s[88:89], 0, v[140:141]
	s_add_i32 m0, s13, 0xe000
	s_nop 0
	global_load_lds_dwordx4 v[216:217], off
	s_waitcnt vmcnt(8)
	s_waitcnt lgkmcnt(0)
	s_barrier
	s_setprio 1
	s_waitcnt lgkmcnt(0)
	v_mfma_f32_16x16x32_bf16 v[126:129], v[146:149], v[184:187], v[126:129]
	v_mfma_f32_16x16x32_bf16 v[122:125], v[160:163], v[184:187], v[122:125]
	v_mfma_f32_16x16x32_bf16 v[118:121], v[146:149], v[192:195], v[118:121]
	v_mfma_f32_16x16x32_bf16 v[114:117], v[160:163], v[192:195], v[114:117]
	v_mfma_f32_16x16x32_bf16 v[110:113], v[146:149], v[200:203], v[110:113]
	v_mfma_f32_16x16x32_bf16 v[106:109], v[160:163], v[200:203], v[106:109]
	v_mfma_f32_16x16x32_bf16 v[102:105], v[146:149], v[208:211], v[102:105]
	v_mfma_f32_16x16x32_bf16 v[98:101], v[160:163], v[208:211], v[98:101]
	v_mfma_f32_16x16x32_bf16 v[126:129], v[156:159], v[188:191], v[126:129]
	v_mfma_f32_16x16x32_bf16 v[122:125], v[164:167], v[188:191], v[122:125]
	v_mfma_f32_16x16x32_bf16 v[118:121], v[156:159], v[196:199], v[118:121]
	v_mfma_f32_16x16x32_bf16 v[114:117], v[164:167], v[196:199], v[114:117]
	v_mfma_f32_16x16x32_bf16 v[110:113], v[156:159], v[204:207], v[110:113]
	v_mfma_f32_16x16x32_bf16 v[106:109], v[164:167], v[204:207], v[106:109]
	v_mfma_f32_16x16x32_bf16 v[102:105], v[156:159], v[212:215], v[102:105]
	v_mfma_f32_16x16x32_bf16 v[98:101], v[164:167], v[212:215], v[98:101]
	s_setprio 0
	s_setprio 1
	v_mfma_f32_16x16x32_bf16 v[62:65], v[168:171], v[184:187], v[62:65]
	v_mfma_f32_16x16x32_bf16 v[58:61], v[176:179], v[184:187], v[58:61]
	v_mfma_f32_16x16x32_bf16 v[54:57], v[168:171], v[192:195], v[54:57]
	v_mfma_f32_16x16x32_bf16 v[50:53], v[176:179], v[192:195], v[50:53]
	v_mfma_f32_16x16x32_bf16 v[46:49], v[168:171], v[200:203], v[46:49]
	v_mfma_f32_16x16x32_bf16 v[42:45], v[176:179], v[200:203], v[42:45]
	v_mfma_f32_16x16x32_bf16 v[38:41], v[168:171], v[208:211], v[38:41]
	v_mfma_f32_16x16x32_bf16 v[34:37], v[176:179], v[208:211], v[34:37]
	v_mfma_f32_16x16x32_bf16 v[62:65], v[172:175], v[188:191], v[62:65]
	v_mfma_f32_16x16x32_bf16 v[58:61], v[180:183], v[188:191], v[58:61]
	v_mfma_f32_16x16x32_bf16 v[54:57], v[172:175], v[196:199], v[54:57]
	v_mfma_f32_16x16x32_bf16 v[50:53], v[180:183], v[196:199], v[50:53]
	v_mfma_f32_16x16x32_bf16 v[46:49], v[172:175], v[204:207], v[46:49]
	v_mfma_f32_16x16x32_bf16 v[42:45], v[180:183], v[204:207], v[42:45]
	v_mfma_f32_16x16x32_bf16 v[38:41], v[172:175], v[212:215], v[38:41]
	v_mfma_f32_16x16x32_bf16 v[34:37], v[180:183], v[212:215], v[34:37]
	s_setprio 0
	s_barrier
	s_add_i32 s3, s33, s12
	v_lshl_add_u64 v[216:217], s[90:91], 0, v[132:133]
	s_mov_b32 m0, s3
	ds_read_b128 v[184:187], v154 offset:16384
	ds_read_b128 v[188:191], v154 offset:17408
	ds_read_b128 v[192:195], v154 offset:18432
	ds_read_b128 v[196:199], v154 offset:19456
	ds_read_b128 v[200:203], v154 offset:20480
	ds_read_b128 v[204:207], v154 offset:21504
	ds_read_b128 v[208:211], v154 offset:22528
	ds_read_b128 v[212:215], v154 offset:23552
	global_load_lds_dwordx4 v[216:217], off
	s_add_i32 m0, s3, 0x2000
	s_add_u32 vcc_lo, s90, 0x40000
	v_lshl_add_u64 v[218:219], s[90:91], 0, v[136:137]
	s_addc_u32 vcc_hi, s91, 0
	s_add_i32 s3, s75, s12
	global_load_lds_dwordx4 v[218:219], off
	v_lshl_add_u64 v[220:221], vcc, 0, v[132:133]
	s_mov_b32 m0, s3
	v_lshl_add_u64 v[222:223], s[92:93], 0, v[134:135]
	global_load_lds_dwordx4 v[220:221], off
	v_lshl_add_u64 v[220:221], vcc, 0, v[136:137]
	s_add_i32 m0, s3, 0x2000
	s_nop 0
	global_load_lds_dwordx4 v[220:221], off
	v_lshl_add_u64 v[220:221], s[92:93], 0, v[130:131]
	s_mov_b32 m0, s13
	s_nop 0
	global_load_lds_dwordx4 v[220:221], off
	s_mov_b32 m0, s34
	s_nop 0
	global_load_lds_dwordx4 v[222:223], off
	s_waitcnt vmcnt(8)
	s_waitcnt lgkmcnt(0)
	s_barrier
; #define PG8_STAGE(bufoff, gbase, voff) do { _Pragma("unroll") for (int _i = 0; _i < 2; ++_i) \
;         __builtin_amdgcn_global_load_lds((const unsigned*)((const char*)(gbase) + (voff)[_i]), (PG8_LAS unsigned*)(lds + (bufoff) + ldsw + _i * 8192), 16, 0, 0); } while (0)
; #define PG8_LDA(dst, b, h) do { _Pragma("unroll") for (int m = 0; m < 4; ++m) _Pragma("unroll") for (int k = 0; k < 2; ++k) dst[m][k] = *(const PG8_LAS bf16x8*)(lds + PG8_SA(b, h) + aoff + m * 2048 + k * 1024); } while (0)
; #define PG8_LDB(dst, b, h) do { _Pragma("unroll") for (int n = 0; n < 2; ++n) _Pragma("unroll") for (int k = 0; k < 2; ++k) dst[n][k] = *(const PG8_LAS bf16x8*)(lds + PG8_SB(b, h) + boff + n * 2048 + k * 1024); } while (0)
; #define PG8_MMA(ai, bj, At, Bt) do { __builtin_amdgcn_s_setprio(1); _Pragma("unroll") for (int m = 0; m < 4; ++m) _Pragma("unroll") for (int n = 0; n < 2; ++n) _Pragma("unroll") for (int k = 0; k < 2; ++k) \
;         acc[ai][bj][m][n] = __builtin_amdgcn_mfma_f32_16x16x32_bf16(Bt[n][k], At[m][k], acc[ai][bj][m][n], 0, 0, 0); __builtin_amdgcn_s_setprio(0); } while (0)
; #define PG8_WAIT_V(n) asm volatile("s_waitcnt vmcnt(" #n ")" ::: "memory")
; #define PG8_WAIT_L(n) asm volatile("s_waitcnt lgkmcnt(" #n ")" ::: "memory")
; #define PG8_BAR __builtin_amdgcn_s_barrier()
; #define PG8_SCHED __builtin_amdgcn_sched_barrier(0)
; template <class Epi, class Sched, bool ALIGN_EPI = false, bool SP2 = false>
; __device__ __forceinline__ void gemm_phase(PG8_LAS unsigned char* lds, const Gemm g, const Sched& S, const Epi& E) {
;     ...
;             PG8_WAIT_V(8); PG8_WAIT_L(0); PG8_BAR; PG8_MMA(1, 0, At, B0); PG8_MMA(1, 1, At, B1); PG8_BAR; PG8_SCHED;
;             PG8_LDB(B0, 1, 0); PG8_LDB(B1, 1, 1); PG8_SCHED; PG8_LDA(At, 1, 0); PG8_STAGE(PG8_SA(0, 1), a2 + hstep, voffA);
;             PG8_WAIT_V(8); PG8_WAIT_L(0); PG8_BAR; PG8_MMA(0, 0, At, B0); PG8_MMA(0, 1, At, B1); PG8_BAR; PG8_SCHED;
	s_setprio 1
	s_waitcnt lgkmcnt(0)
	v_mfma_f32_16x16x32_bf16 v[94:97], v[146:149], v[184:187], v[94:97]
	v_mfma_f32_16x16x32_bf16 v[90:93], v[160:163], v[184:187], v[90:93]
	v_mfma_f32_16x16x32_bf16 v[86:89], v[146:149], v[192:195], v[86:89]
	v_mfma_f32_16x16x32_bf16 v[82:85], v[160:163], v[192:195], v[82:85]
	v_mfma_f32_16x16x32_bf16 v[78:81], v[146:149], v[200:203], v[78:81]
	v_mfma_f32_16x16x32_bf16 v[74:77], v[160:163], v[200:203], v[74:77]
	v_mfma_f32_16x16x32_bf16 v[70:73], v[146:149], v[208:211], v[70:73]
	v_mfma_f32_16x16x32_bf16 v[66:69], v[160:163], v[208:211], v[66:69]
	v_mfma_f32_16x16x32_bf16 v[94:97], v[156:159], v[188:191], v[94:97]
	v_mfma_f32_16x16x32_bf16 v[90:93], v[164:167], v[188:191], v[90:93]
	v_mfma_f32_16x16x32_bf16 v[86:89], v[156:159], v[196:199], v[86:89]
	v_mfma_f32_16x16x32_bf16 v[82:85], v[164:167], v[196:199], v[82:85]
	v_mfma_f32_16x16x32_bf16 v[78:81], v[156:159], v[204:207], v[78:81]
	v_mfma_f32_16x16x32_bf16 v[74:77], v[164:167], v[204:207], v[74:77]
	v_mfma_f32_16x16x32_bf16 v[70:73], v[156:159], v[212:215], v[70:73]
	v_mfma_f32_16x16x32_bf16 v[66:69], v[164:167], v[212:215], v[66:69]
	s_setprio 0
	s_setprio 1
	v_mfma_f32_16x16x32_bf16 v[30:33], v[168:171], v[184:187], v[30:33]
	v_mfma_f32_16x16x32_bf16 v[26:29], v[176:179], v[184:187], v[26:29]
	v_mfma_f32_16x16x32_bf16 v[22:25], v[168:171], v[192:195], v[22:25]
	v_mfma_f32_16x16x32_bf16 v[18:21], v[176:179], v[192:195], v[18:21]
	v_mfma_f32_16x16x32_bf16 v[14:17], v[168:171], v[200:203], v[14:17]
	v_mfma_f32_16x16x32_bf16 v[10:13], v[176:179], v[200:203], v[10:13]
	v_mfma_f32_16x16x32_bf16 v[6:9], v[168:171], v[208:211], v[6:9]
	v_mfma_f32_16x16x32_bf16 v[2:5], v[176:179], v[208:211], v[2:5]
	v_mfma_f32_16x16x32_bf16 v[30:33], v[172:175], v[188:191], v[30:33]
	v_mfma_f32_16x16x32_bf16 v[26:29], v[180:183], v[188:191], v[26:29]
	v_mfma_f32_16x16x32_bf16 v[22:25], v[172:175], v[196:199], v[22:25]
	v_mfma_f32_16x16x32_bf16 v[18:21], v[180:183], v[196:199], v[18:21]
	v_mfma_f32_16x16x32_bf16 v[14:17], v[172:175], v[204:207], v[14:17]
	v_mfma_f32_16x16x32_bf16 v[10:13], v[180:183], v[204:207], v[10:13]
	v_mfma_f32_16x16x32_bf16 v[6:9], v[172:175], v[212:215], v[6:9]
	v_mfma_f32_16x16x32_bf16 v[2:5], v[180:183], v[212:215], v[2:5]
	s_setprio 0
	s_barrier
	s_add_i32 s3, 0, 0x18000
	s_add_i32 s97, 0, 0x1c000
	v_add_u32_e32 v164, s3, v150
	v_add_u32_e32 v180, s97, v150
	ds_read_b128 v[146:149], v164
	ds_read_b128 v[156:159], v164 offset:1024
	ds_read_b128 v[160:163], v164 offset:2048
	ds_read_b128 v[164:167], v164 offset:3072
	ds_read_b128 v[168:171], v180
	ds_read_b128 v[172:175], v180 offset:1024
	ds_read_b128 v[176:179], v180 offset:2048
	ds_read_b128 v[180:183], v180 offset:3072
	s_add_u32 s92, s92, 0x40000
	s_addc_u32 s93, s93, 0
	s_mov_b32 m0, s35
	v_lshl_add_u64 v[224:225], s[92:93], 0, v[130:131]
	ds_read_b128 v[184:187], v154 offset:32768
	ds_read_b128 v[188:191], v154 offset:33792
	ds_read_b128 v[192:195], v154 offset:34816
	ds_read_b128 v[196:199], v154 offset:35840
	ds_read_b128 v[200:203], v154 offset:36864
	ds_read_b128 v[204:207], v154 offset:37888
	ds_read_b128 v[208:211], v154 offset:38912
	ds_read_b128 v[212:215], v154 offset:39936
	global_load_lds_dwordx4 v[224:225], off
	v_lshl_add_u64 v[224:225], s[92:93], 0, v[134:135]
	s_mov_b32 m0, s70
	s_nop 0
	global_load_lds_dwordx4 v[224:225], off
	s_waitcnt vmcnt(8)
	s_waitcnt lgkmcnt(0)
	s_barrier
	s_setprio 1
	s_waitcnt lgkmcnt(0)
	v_mfma_f32_16x16x32_bf16 v[126:129], v[146:149], v[184:187], v[126:129]
	v_mfma_f32_16x16x32_bf16 v[122:125], v[160:163], v[184:187], v[122:125]
	v_mfma_f32_16x16x32_bf16 v[118:121], v[146:149], v[192:195], v[118:121]
	v_mfma_f32_16x16x32_bf16 v[114:117], v[160:163], v[192:195], v[114:117]
	v_mfma_f32_16x16x32_bf16 v[110:113], v[146:149], v[200:203], v[110:113]
	v_mfma_f32_16x16x32_bf16 v[106:109], v[160:163], v[200:203], v[106:109]
	v_mfma_f32_16x16x32_bf16 v[102:105], v[146:149], v[208:211], v[102:105]
	v_mfma_f32_16x16x32_bf16 v[98:101], v[160:163], v[208:211], v[98:101]
	v_mfma_f32_16x16x32_bf16 v[126:129], v[156:159], v[188:191], v[126:129]
	v_mfma_f32_16x16x32_bf16 v[122:125], v[164:167], v[188:191], v[122:125]
	v_mfma_f32_16x16x32_bf16 v[118:121], v[156:159], v[196:199], v[118:121]
	v_mfma_f32_16x16x32_bf16 v[114:117], v[164:167], v[196:199], v[114:117]
	v_mfma_f32_16x16x32_bf16 v[110:113], v[156:159], v[204:207], v[110:113]
	v_mfma_f32_16x16x32_bf16 v[106:109], v[164:167], v[204:207], v[106:109]
	v_mfma_f32_16x16x32_bf16 v[102:105], v[156:159], v[212:215], v[102:105]
	v_mfma_f32_16x16x32_bf16 v[98:101], v[164:167], v[212:215], v[98:101]
	s_setprio 0
	s_setprio 1
	v_mfma_f32_16x16x32_bf16 v[62:65], v[168:171], v[184:187], v[62:65]
	v_mfma_f32_16x16x32_bf16 v[58:61], v[176:179], v[184:187], v[58:61]
	v_mfma_f32_16x16x32_bf16 v[54:57], v[168:171], v[192:195], v[54:57]
	v_mfma_f32_16x16x32_bf16 v[50:53], v[176:179], v[192:195], v[50:53]
	v_mfma_f32_16x16x32_bf16 v[46:49], v[168:171], v[200:203], v[46:49]
	v_mfma_f32_16x16x32_bf16 v[42:45], v[176:179], v[200:203], v[42:45]
	v_mfma_f32_16x16x32_bf16 v[38:41], v[168:171], v[208:211], v[38:41]
	v_mfma_f32_16x16x32_bf16 v[34:37], v[176:179], v[208:211], v[34:37]
	v_mfma_f32_16x16x32_bf16 v[62:65], v[172:175], v[188:191], v[62:65]
	v_mfma_f32_16x16x32_bf16 v[58:61], v[180:183], v[188:191], v[58:61]
	v_mfma_f32_16x16x32_bf16 v[54:57], v[172:175], v[196:199], v[54:57]
	v_mfma_f32_16x16x32_bf16 v[50:53], v[180:183], v[196:199], v[50:53]
	v_mfma_f32_16x16x32_bf16 v[46:49], v[172:175], v[204:207], v[46:49]
	v_mfma_f32_16x16x32_bf16 v[42:45], v[180:183], v[204:207], v[42:45]
	v_mfma_f32_16x16x32_bf16 v[38:41], v[172:175], v[212:215], v[38:41]
	v_mfma_f32_16x16x32_bf16 v[34:37], v[180:183], v[212:215], v[34:37]
	s_setprio 0
	s_barrier
; #define PG8_STAGE(bufoff, gbase, voff) do { _Pragma("unroll") for (int _i = 0; _i < 2; ++_i) \
;         __builtin_amdgcn_global_load_lds((const unsigned*)((const char*)(gbase) + (voff)[_i]), (PG8_LAS unsigned*)(lds + (bufoff) + ldsw + _i * 8192), 16, 0, 0); } while (0)
; #define PG8_LDA(dst, b, h) do { _Pragma("unroll") for (int m = 0; m < 4; ++m) _Pragma("unroll") for (int k = 0; k < 2; ++k) dst[m][k] = *(const PG8_LAS bf16x8*)(lds + PG8_SA(b, h) + aoff + m * 2048 + k * 1024); } while (0)
; #define PG8_MMA(ai, bj, At, Bt) do { __builtin_amdgcn_s_setprio(1); _Pragma("unroll") for (int m = 0; m < 4; ++m) _Pragma("unroll") for (int n = 0; n < 2; ++n) _Pragma("unroll") for (int k = 0; k < 2; ++k) \
;         acc[ai][bj][m][n] = __builtin_amdgcn_mfma_f32_16x16x32_bf16(Bt[n][k], At[m][k], acc[ai][bj][m][n], 0, 0, 0); __builtin_amdgcn_s_setprio(0); } while (0)
; #define PG8_WAIT_V(n) asm volatile("s_waitcnt vmcnt(" #n ")" ::: "memory")
; #define PG8_WAIT_L(n) asm volatile("s_waitcnt lgkmcnt(" #n ")" ::: "memory")
; #define PG8_BAR __builtin_amdgcn_s_barrier()
; #define PG8_SCHED __builtin_amdgcn_sched_barrier(0)
; template <class Epi, class Sched, bool ALIGN_EPI = false, bool SP2 = false>
; __device__ __forceinline__ void gemm_phase(PG8_LAS unsigned char* lds, const Gemm g, const Sched& S, const Epi& E) {
;     ...
;         for (int t = 0; t < nt; t += 2) {
;     ...
;             PG8_LDA(At, 1, 1); PG8_STAGE(PG8_SB(1, 0), b3, voffB); PG8_STAGE(PG8_SB(1, 1), b3 + hstep, voffB); PG8_STAGE(PG8_SA(1, 0), a3, voffA);
;             PG8_WAIT_V(8); PG8_WAIT_L(0); PG8_BAR; PG8_MMA(1, 0, At, B0); PG8_MMA(1, 1, At, B1); PG8_BAR; PG8_SCHED;
	s_add_i32 s3, s3, s12
	v_lshl_add_u64 v[216:217], v[216:217], 0, s[28:29]
	s_mov_b32 m0, s3
	ds_read_b128 v[184:187], v154 offset:49152
	ds_read_b128 v[188:191], v154 offset:50176
	ds_read_b128 v[192:195], v154 offset:51200
	ds_read_b128 v[196:199], v154 offset:52224
	ds_read_b128 v[200:203], v154 offset:53248
	ds_read_b128 v[204:207], v154 offset:54272
	ds_read_b128 v[208:211], v154 offset:55296
	ds_read_b128 v[212:215], v154 offset:56320
	global_load_lds_dwordx4 v[216:217], off
	s_add_i32 m0, s3, 0x2000
	s_add_u32 s90, s90, 0x40080
	v_lshl_add_u64 v[216:217], v[218:219], 0, s[28:29]
	s_addc_u32 s91, s91, 0
	s_add_i32 s3, s97, s12
	global_load_lds_dwordx4 v[216:217], off
	v_lshl_add_u64 v[216:217], s[90:91], 0, v[132:133]
	s_mov_b32 m0, s3
	s_nop 0
	global_load_lds_dwordx4 v[216:217], off
	v_lshl_add_u64 v[216:217], s[90:91], 0, v[136:137]
	s_add_i32 m0, s3, 0x2000
	s_nop 0
	global_load_lds_dwordx4 v[216:217], off
	v_lshl_add_u64 v[216:217], v[220:221], 0, s[28:29]
	s_mov_b32 m0, s71
	s_nop 0
	global_load_lds_dwordx4 v[216:217], off
	v_lshl_add_u64 v[216:217], v[222:223], 0, s[28:29]
	s_mov_b32 m0, s72
	s_nop 0
	global_load_lds_dwordx4 v[216:217], off
	s_waitcnt vmcnt(8)
	s_waitcnt lgkmcnt(0)
	s_barrier
	s_setprio 1
	s_waitcnt lgkmcnt(0)
	v_mfma_f32_16x16x32_bf16 v[94:97], v[146:149], v[184:187], v[94:97]
	s_add_i32 s96, s96, 2
	s_add_u32 s88, s88, 0x100
	s_addc_u32 s89, s89, 0
	s_add_u32 s81, s81, 0x100
	s_addc_u32 s87, s87, 0
	s_cmp_gt_u32 s96, 13
	v_mfma_f32_16x16x32_bf16 v[90:93], v[160:163], v[184:187], v[90:93]
	v_mfma_f32_16x16x32_bf16 v[86:89], v[146:149], v[192:195], v[86:89]
	v_mfma_f32_16x16x32_bf16 v[82:85], v[160:163], v[192:195], v[82:85]
	v_mfma_f32_16x16x32_bf16 v[78:81], v[146:149], v[200:203], v[78:81]
	v_mfma_f32_16x16x32_bf16 v[74:77], v[160:163], v[200:203], v[74:77]
	v_mfma_f32_16x16x32_bf16 v[70:73], v[146:149], v[208:211], v[70:73]
	v_mfma_f32_16x16x32_bf16 v[66:69], v[160:163], v[208:211], v[66:69]
	v_mfma_f32_16x16x32_bf16 v[94:97], v[156:159], v[188:191], v[94:97]
	v_mfma_f32_16x16x32_bf16 v[90:93], v[164:167], v[188:191], v[90:93]
	v_mfma_f32_16x16x32_bf16 v[86:89], v[156:159], v[196:199], v[86:89]
	v_mfma_f32_16x16x32_bf16 v[82:85], v[164:167], v[196:199], v[82:85]
	v_mfma_f32_16x16x32_bf16 v[78:81], v[156:159], v[204:207], v[78:81]
	v_mfma_f32_16x16x32_bf16 v[74:77], v[164:167], v[204:207], v[74:77]
	v_mfma_f32_16x16x32_bf16 v[70:73], v[156:159], v[212:215], v[70:73]
	v_mfma_f32_16x16x32_bf16 v[66:69], v[164:167], v[212:215], v[66:69]
	s_setprio 0
	s_setprio 1
	v_mfma_f32_16x16x32_bf16 v[30:33], v[168:171], v[184:187], v[30:33]
	v_mfma_f32_16x16x32_bf16 v[26:29], v[176:179], v[184:187], v[26:29]
	v_mfma_f32_16x16x32_bf16 v[22:25], v[168:171], v[192:195], v[22:25]
	v_mfma_f32_16x16x32_bf16 v[18:21], v[176:179], v[192:195], v[18:21]
	v_mfma_f32_16x16x32_bf16 v[14:17], v[168:171], v[200:203], v[14:17]
	v_mfma_f32_16x16x32_bf16 v[10:13], v[176:179], v[200:203], v[10:13]
	v_mfma_f32_16x16x32_bf16 v[6:9], v[168:171], v[208:211], v[6:9]
	v_mfma_f32_16x16x32_bf16 v[2:5], v[176:179], v[208:211], v[2:5]
	v_mfma_f32_16x16x32_bf16 v[30:33], v[172:175], v[188:191], v[30:33]
	v_mfma_f32_16x16x32_bf16 v[26:29], v[180:183], v[188:191], v[26:29]
	v_mfma_f32_16x16x32_bf16 v[22:25], v[172:175], v[196:199], v[22:25]
	v_mfma_f32_16x16x32_bf16 v[18:21], v[180:183], v[196:199], v[18:21]
	v_mfma_f32_16x16x32_bf16 v[14:17], v[172:175], v[204:207], v[14:17]
	v_mfma_f32_16x16x32_bf16 v[10:13], v[180:183], v[204:207], v[10:13]
	v_mfma_f32_16x16x32_bf16 v[6:9], v[172:175], v[212:215], v[6:9]
	v_mfma_f32_16x16x32_bf16 v[2:5], v[180:183], v[212:215], v[2:5]
	s_setprio 0
	s_barrier
	s_cbranch_scc0 .LBB0_270
	s_and_b64 vcc, exec, s[56:57]
	s_cbranch_vccz .LBB0_273
	s_barrier

; #define PG8_STAGE(bufoff, gbase, voff) do { _Pragma("unroll") for (int _i = 0; _i < 2; ++_i) \
;         __builtin_amdgcn_global_load_lds((const unsigned*)((const char*)(gbase) + (voff)[_i]), (PG8_LAS unsigned*)(lds + (bufoff) + ldsw + _i * 8192), 16, 0, 0); } while (0)
; #define PG8_LDA(dst, b, h) do { _Pragma("unroll") for (int m = 0; m < 4; ++m) _Pragma("unroll") for (int k = 0; k < 2; ++k) dst[m][k] = *(const PG8_LAS bf16x8*)(lds + PG8_SA(b, h) + aoff + m * 2048 + k * 1024); } while (0)
; #define PG8_LDB(dst, b, h) do { _Pragma("unroll") for (int n = 0; n < 2; ++n) _Pragma("unroll") for (int k = 0; k < 2; ++k) dst[n][k] = *(const PG8_LAS bf16x8*)(lds + PG8_SB(b, h) + boff + n * 2048 + k * 1024); } while (0)
; #define PG8_MMA(ai, bj, At, Bt) do { __builtin_amdgcn_s_setprio(1); _Pragma("unroll") for (int m = 0; m < 4; ++m) _Pragma("unroll") for (int n = 0; n < 2; ++n) _Pragma("unroll") for (int k = 0; k < 2; ++k) \
;         acc[ai][bj][m][n] = __builtin_amdgcn_mfma_f32_16x16x32_bf16(Bt[n][k], At[m][k], acc[ai][bj][m][n], 0, 0, 0); __builtin_amdgcn_s_setprio(0); } while (0)
; #define PG8_WAIT_V(n) asm volatile("s_waitcnt vmcnt(" #n ")" ::: "memory")
; #define PG8_WAIT_L(n) asm volatile("s_waitcnt lgkmcnt(" #n ")" ::: "memory")
; #define PG8_BAR __builtin_amdgcn_s_barrier()
; #define PG8_SCHED __builtin_amdgcn_sched_barrier(0)
; template <class Epi, class Sched, bool ALIGN_EPI = false, bool SP2 = false>
; __device__ __forceinline__ void gemm_phase(PG8_LAS unsigned char* lds, const Gemm g, const Sched& S, const Epi& E) {
;     ...
;             PG8_LDB(B0, 0, 0); PG8_LDB(B1, 0, 1); PG8_SCHED; PG8_LDA(At, 0, 0); PG8_STAGE(PG8_SA(1, 1), a1 + hstep, voffA);
;             PG8_WAIT_V(8); PG8_WAIT_L(0); PG8_BAR; PG8_MMA(0, 0, At, B0); PG8_MMA(0, 1, At, B1); PG8_BAR; PG8_SCHED;
;             PG8_LDA(At, 0, 1); PG8_STAGE(PG8_SB(0, 0), b2, voffB); PG8_STAGE(PG8_SB(0, 1), b2 + hstep, voffB); PG8_STAGE(PG8_SA(0, 0), a2, voffA);
;             PG8_WAIT_V(8); PG8_WAIT_L(0); PG8_BAR; PG8_MMA(1, 0, At, B0); PG8_MMA(1, 1, At, B1); PG8_BAR; PG8_SCHED;
.LBB0_1026:
	v_add_u32_e32 v149, s33, v146
	ds_read_b128 v[154:157], v149
	ds_read_b128 v[158:161], v149 offset:1024
	ds_read_b128 v[162:165], v149 offset:2048
	ds_read_b128 v[166:169], v149 offset:3072
	v_add_u32_e32 v149, s59, v146
	s_add_u32 s3, s8, s46
	ds_read_b128 v[172:175], v149
	ds_read_b128 v[176:179], v149 offset:1024
	ds_read_b128 v[180:183], v149 offset:2048
	ds_read_b128 v[184:187], v149 offset:3072
	s_addc_u32 s48, s9, s47
	s_add_u32 s3, s3, 0x100
	s_addc_u32 s48, s48, 0
	s_add_u32 s60, s0, s46
	s_addc_u32 s49, s1, s47
	s_cmpk_eq_i32 s46, 0x700
	s_cselect_b32 s51, s26, s48
	s_cselect_b32 s50, s27, s3
	s_cselect_b32 s49, s37, s49
	s_cselect_b32 s48, s39, s60
	v_lshl_add_u64 v[150:151], v[142:143], 0, s[46:47]
	s_add_i32 m0, s35, 0xc000
	ds_read_b128 v[188:191], v147
	ds_read_b128 v[192:195], v147 offset:1024
	ds_read_b128 v[196:199], v147 offset:2048
	ds_read_b128 v[200:203], v147 offset:3072
	ds_read_b128 v[204:207], v147 offset:4096
	ds_read_b128 v[208:211], v147 offset:5120
	ds_read_b128 v[212:215], v147 offset:6144
	ds_read_b128 v[216:219], v147 offset:7168
	global_load_lds_dwordx4 v[150:151], off
	v_lshl_add_u64 v[150:151], v[144:145], 0, s[46:47]
	s_add_i32 m0, s35, 0xe000
	s_nop 0
	global_load_lds_dwordx4 v[150:151], off
	s_waitcnt vmcnt(8)
	s_waitcnt lgkmcnt(0)
	s_barrier
	s_setprio 1
	s_waitcnt lgkmcnt(0)
	v_mfma_f32_16x16x32_bf16 v[126:129], v[154:157], v[188:191], v[126:129]
	v_mfma_f32_16x16x32_bf16 v[122:125], v[162:165], v[188:191], v[122:125]
	v_mfma_f32_16x16x32_bf16 v[110:113], v[154:157], v[196:199], v[110:113]
	v_mfma_f32_16x16x32_bf16 v[106:109], v[162:165], v[196:199], v[106:109]
	v_mfma_f32_16x16x32_bf16 v[94:97], v[154:157], v[204:207], v[94:97]
	v_mfma_f32_16x16x32_bf16 v[90:93], v[162:165], v[204:207], v[90:93]
	v_mfma_f32_16x16x32_bf16 v[78:81], v[154:157], v[212:215], v[78:81]
	v_mfma_f32_16x16x32_bf16 v[74:77], v[162:165], v[212:215], v[74:77]
	v_mfma_f32_16x16x32_bf16 v[126:129], v[158:161], v[192:195], v[126:129]
	v_mfma_f32_16x16x32_bf16 v[122:125], v[166:169], v[192:195], v[122:125]
	v_mfma_f32_16x16x32_bf16 v[110:113], v[158:161], v[200:203], v[110:113]
	v_mfma_f32_16x16x32_bf16 v[106:109], v[166:169], v[200:203], v[106:109]
	v_mfma_f32_16x16x32_bf16 v[94:97], v[158:161], v[208:211], v[94:97]
	v_mfma_f32_16x16x32_bf16 v[90:93], v[166:169], v[208:211], v[90:93]
	v_mfma_f32_16x16x32_bf16 v[78:81], v[158:161], v[216:219], v[78:81]
	v_mfma_f32_16x16x32_bf16 v[74:77], v[166:169], v[216:219], v[74:77]
	s_setprio 0
	s_setprio 1
	v_mfma_f32_16x16x32_bf16 v[118:121], v[172:175], v[188:191], v[118:121]
	v_mfma_f32_16x16x32_bf16 v[114:117], v[180:183], v[188:191], v[114:117]
	v_mfma_f32_16x16x32_bf16 v[102:105], v[172:175], v[196:199], v[102:105]
	v_mfma_f32_16x16x32_bf16 v[98:101], v[180:183], v[196:199], v[98:101]
	v_mfma_f32_16x16x32_bf16 v[86:89], v[172:175], v[204:207], v[86:89]
	v_mfma_f32_16x16x32_bf16 v[82:85], v[180:183], v[204:207], v[82:85]
	v_mfma_f32_16x16x32_bf16 v[70:73], v[172:175], v[212:215], v[70:73]
	v_mfma_f32_16x16x32_bf16 v[66:69], v[180:183], v[212:215], v[66:69]
	v_mfma_f32_16x16x32_bf16 v[118:121], v[176:179], v[192:195], v[118:121]
	v_mfma_f32_16x16x32_bf16 v[114:117], v[184:187], v[192:195], v[114:117]
	v_mfma_f32_16x16x32_bf16 v[102:105], v[176:179], v[200:203], v[102:105]
	v_mfma_f32_16x16x32_bf16 v[98:101], v[184:187], v[200:203], v[98:101]
	v_mfma_f32_16x16x32_bf16 v[86:89], v[176:179], v[208:211], v[86:89]
	v_mfma_f32_16x16x32_bf16 v[82:85], v[184:187], v[208:211], v[82:85]
	v_mfma_f32_16x16x32_bf16 v[70:73], v[176:179], v[216:219], v[70:73]
	v_mfma_f32_16x16x32_bf16 v[66:69], v[184:187], v[216:219], v[66:69]
	s_setprio 0
	s_barrier
	s_add_i32 s3, s33, s31
	v_lshl_add_u64 v[150:151], s[48:49], 0, v[130:131]
	s_mov_b32 m0, s3
	ds_read_b128 v[188:191], v147 offset:16384
	ds_read_b128 v[192:195], v147 offset:17408
	ds_read_b128 v[196:199], v147 offset:18432
	ds_read_b128 v[200:203], v147 offset:19456
	ds_read_b128 v[204:207], v147 offset:20480
	ds_read_b128 v[208:211], v147 offset:21504
	ds_read_b128 v[212:215], v147 offset:22528
	ds_read_b128 v[216:219], v147 offset:23552
	global_load_lds_dwordx4 v[150:151], off
	s_add_i32 m0, s3, 0x2000
	s_add_u32 s60, s48, 0x40000
	v_lshl_add_u64 v[220:221], s[48:49], 0, v[132:133]
	s_addc_u32 s61, s49, 0
	s_add_i32 s3, s59, s31
	global_load_lds_dwordx4 v[220:221], off
	v_lshl_add_u64 v[222:223], s[60:61], 0, v[130:131]
	s_mov_b32 m0, s3
	v_lshl_add_u64 v[224:225], s[50:51], 0, v[132:133]
	global_load_lds_dwordx4 v[222:223], off
	v_lshl_add_u64 v[222:223], s[60:61], 0, v[132:133]
	s_add_i32 m0, s3, 0x2000
	s_nop 0
	global_load_lds_dwordx4 v[222:223], off
	v_lshl_add_u64 v[222:223], s[50:51], 0, v[130:131]
	s_mov_b32 m0, s35
	s_nop 0
	global_load_lds_dwordx4 v[222:223], off
	s_mov_b32 m0, s53
	s_nop 0
	global_load_lds_dwordx4 v[224:225], off
	s_waitcnt vmcnt(8)
	s_waitcnt lgkmcnt(0)
	s_barrier
; #define PG8_STAGE(bufoff, gbase, voff) do { _Pragma("unroll") for (int _i = 0; _i < 2; ++_i) \
;         __builtin_amdgcn_global_load_lds((const unsigned*)((const char*)(gbase) + (voff)[_i]), (PG8_LAS unsigned*)(lds + (bufoff) + ldsw + _i * 8192), 16, 0, 0); } while (0)
; #define PG8_LDA(dst, b, h) do { _Pragma("unroll") for (int m = 0; m < 4; ++m) _Pragma("unroll") for (int k = 0; k < 2; ++k) dst[m][k] = *(const PG8_LAS bf16x8*)(lds + PG8_SA(b, h) + aoff + m * 2048 + k * 1024); } while (0)
; #define PG8_LDB(dst, b, h) do { _Pragma("unroll") for (int n = 0; n < 2; ++n) _Pragma("unroll") for (int k = 0; k < 2; ++k) dst[n][k] = *(const PG8_LAS bf16x8*)(lds + PG8_SB(b, h) + boff + n * 2048 + k * 1024); } while (0)
; #define PG8_MMA(ai, bj, At, Bt) do { __builtin_amdgcn_s_setprio(1); _Pragma("unroll") for (int m = 0; m < 4; ++m) _Pragma("unroll") for (int n = 0; n < 2; ++n) _Pragma("unroll") for (int k = 0; k < 2; ++k) \
;         acc[ai][bj][m][n] = __builtin_amdgcn_mfma_f32_16x16x32_bf16(Bt[n][k], At[m][k], acc[ai][bj][m][n], 0, 0, 0); __builtin_amdgcn_s_setprio(0); } while (0)
; #define PG8_WAIT_V(n) asm volatile("s_waitcnt vmcnt(" #n ")" ::: "memory")
; #define PG8_WAIT_L(n) asm volatile("s_waitcnt lgkmcnt(" #n ")" ::: "memory")
; #define PG8_BAR __builtin_amdgcn_s_barrier()
; #define PG8_SCHED __builtin_amdgcn_sched_barrier(0)
; template <class Epi, class Sched, bool ALIGN_EPI = false, bool SP2 = false>
; __device__ __forceinline__ void gemm_phase(PG8_LAS unsigned char* lds, const Gemm g, const Sched& S, const Epi& E) {
;     ...
;             PG8_WAIT_V(8); PG8_WAIT_L(0); PG8_BAR; PG8_MMA(1, 0, At, B0); PG8_MMA(1, 1, At, B1); PG8_BAR; PG8_SCHED;
;             PG8_LDB(B0, 1, 0); PG8_LDB(B1, 1, 1); PG8_SCHED; PG8_LDA(At, 1, 0); PG8_STAGE(PG8_SA(0, 1), a2 + hstep, voffA);
;             PG8_WAIT_V(8); PG8_WAIT_L(0); PG8_BAR; PG8_MMA(0, 0, At, B0); PG8_MMA(0, 1, At, B1); PG8_BAR; PG8_SCHED;
	s_setprio 1
	s_waitcnt lgkmcnt(0)
	v_mfma_f32_16x16x32_bf16 v[62:65], v[154:157], v[188:191], v[62:65]
	v_mfma_f32_16x16x32_bf16 v[58:61], v[162:165], v[188:191], v[58:61]
	v_mfma_f32_16x16x32_bf16 v[46:49], v[154:157], v[196:199], v[46:49]
	v_mfma_f32_16x16x32_bf16 v[42:45], v[162:165], v[196:199], v[42:45]
	v_mfma_f32_16x16x32_bf16 v[30:33], v[154:157], v[204:207], v[30:33]
	v_mfma_f32_16x16x32_bf16 v[26:29], v[162:165], v[204:207], v[26:29]
	v_mfma_f32_16x16x32_bf16 v[14:17], v[154:157], v[212:215], v[14:17]
	v_mfma_f32_16x16x32_bf16 v[10:13], v[162:165], v[212:215], v[10:13]
	v_mfma_f32_16x16x32_bf16 v[62:65], v[158:161], v[192:195], v[62:65]
	v_mfma_f32_16x16x32_bf16 v[58:61], v[166:169], v[192:195], v[58:61]
	v_mfma_f32_16x16x32_bf16 v[46:49], v[158:161], v[200:203], v[46:49]
	v_mfma_f32_16x16x32_bf16 v[42:45], v[166:169], v[200:203], v[42:45]
	v_mfma_f32_16x16x32_bf16 v[30:33], v[158:161], v[208:211], v[30:33]
	v_mfma_f32_16x16x32_bf16 v[26:29], v[166:169], v[208:211], v[26:29]
	v_mfma_f32_16x16x32_bf16 v[14:17], v[158:161], v[216:219], v[14:17]
	v_mfma_f32_16x16x32_bf16 v[10:13], v[166:169], v[216:219], v[10:13]
	s_setprio 0
	s_setprio 1
	v_mfma_f32_16x16x32_bf16 v[54:57], v[172:175], v[188:191], v[54:57]
	v_mfma_f32_16x16x32_bf16 v[50:53], v[180:183], v[188:191], v[50:53]
	v_mfma_f32_16x16x32_bf16 v[38:41], v[172:175], v[196:199], v[38:41]
	v_mfma_f32_16x16x32_bf16 v[34:37], v[180:183], v[196:199], v[34:37]
	v_mfma_f32_16x16x32_bf16 v[22:25], v[172:175], v[204:207], v[22:25]
	v_mfma_f32_16x16x32_bf16 v[18:21], v[180:183], v[204:207], v[18:21]
	v_mfma_f32_16x16x32_bf16 v[6:9], v[172:175], v[212:215], v[6:9]
	v_mfma_f32_16x16x32_bf16 v[2:5], v[180:183], v[212:215], v[2:5]
	v_mfma_f32_16x16x32_bf16 v[54:57], v[176:179], v[192:195], v[54:57]
	v_mfma_f32_16x16x32_bf16 v[50:53], v[184:187], v[192:195], v[50:53]
	v_mfma_f32_16x16x32_bf16 v[38:41], v[176:179], v[200:203], v[38:41]
	v_mfma_f32_16x16x32_bf16 v[34:37], v[184:187], v[200:203], v[34:37]
	v_mfma_f32_16x16x32_bf16 v[22:25], v[176:179], v[208:211], v[22:25]
	v_mfma_f32_16x16x32_bf16 v[18:21], v[184:187], v[208:211], v[18:21]
	v_mfma_f32_16x16x32_bf16 v[6:9], v[176:179], v[216:219], v[6:9]
	v_mfma_f32_16x16x32_bf16 v[2:5], v[184:187], v[216:219], v[2:5]
	s_setprio 0
	s_barrier
	s_add_i32 s3, 0, 0x18000
	v_add_u32_e32 v149, s3, v146
	s_add_i32 s60, 0, 0x1c000
	ds_read_b128 v[154:157], v149
	ds_read_b128 v[158:161], v149 offset:1024
	ds_read_b128 v[162:165], v149 offset:2048
	ds_read_b128 v[166:169], v149 offset:3072
	v_add_u32_e32 v149, s60, v146
	ds_read_b128 v[172:175], v149
	ds_read_b128 v[176:179], v149 offset:1024
	ds_read_b128 v[180:183], v149 offset:2048
	ds_read_b128 v[184:187], v149 offset:3072
	s_add_u32 s50, s50, 0x40000
	s_addc_u32 s51, s51, 0
	s_mov_b32 m0, s54
	v_lshl_add_u64 v[226:227], s[50:51], 0, v[130:131]
	ds_read_b128 v[188:191], v147 offset:32768
	ds_read_b128 v[192:195], v147 offset:33792
	ds_read_b128 v[196:199], v147 offset:34816
	ds_read_b128 v[200:203], v147 offset:35840
	ds_read_b128 v[204:207], v147 offset:36864
	ds_read_b128 v[208:211], v147 offset:37888
	ds_read_b128 v[212:215], v147 offset:38912
	ds_read_b128 v[216:219], v147 offset:39936
	global_load_lds_dwordx4 v[226:227], off
	v_lshl_add_u64 v[226:227], s[50:51], 0, v[132:133]
	s_mov_b32 m0, s55
	s_nop 0
	global_load_lds_dwordx4 v[226:227], off
	s_waitcnt vmcnt(8)
	s_waitcnt lgkmcnt(0)
	s_barrier
	s_setprio 1
	s_waitcnt lgkmcnt(0)
	v_mfma_f32_16x16x32_bf16 v[126:129], v[154:157], v[188:191], v[126:129]
	v_mfma_f32_16x16x32_bf16 v[122:125], v[162:165], v[188:191], v[122:125]
	v_mfma_f32_16x16x32_bf16 v[110:113], v[154:157], v[196:199], v[110:113]
	v_mfma_f32_16x16x32_bf16 v[106:109], v[162:165], v[196:199], v[106:109]
	v_mfma_f32_16x16x32_bf16 v[94:97], v[154:157], v[204:207], v[94:97]
	v_mfma_f32_16x16x32_bf16 v[90:93], v[162:165], v[204:207], v[90:93]
	v_mfma_f32_16x16x32_bf16 v[78:81], v[154:157], v[212:215], v[78:81]
	v_mfma_f32_16x16x32_bf16 v[74:77], v[162:165], v[212:215], v[74:77]
	v_mfma_f32_16x16x32_bf16 v[126:129], v[158:161], v[192:195], v[126:129]
	v_mfma_f32_16x16x32_bf16 v[122:125], v[166:169], v[192:195], v[122:125]
	v_mfma_f32_16x16x32_bf16 v[110:113], v[158:161], v[200:203], v[110:113]
	v_mfma_f32_16x16x32_bf16 v[106:109], v[166:169], v[200:203], v[106:109]
	v_mfma_f32_16x16x32_bf16 v[94:97], v[158:161], v[208:211], v[94:97]
	v_mfma_f32_16x16x32_bf16 v[90:93], v[166:169], v[208:211], v[90:93]
	v_mfma_f32_16x16x32_bf16 v[78:81], v[158:161], v[216:219], v[78:81]
	v_mfma_f32_16x16x32_bf16 v[74:77], v[166:169], v[216:219], v[74:77]
	s_setprio 0
	s_setprio 1
	v_mfma_f32_16x16x32_bf16 v[118:121], v[172:175], v[188:191], v[118:121]
	v_mfma_f32_16x16x32_bf16 v[114:117], v[180:183], v[188:191], v[114:117]
	v_mfma_f32_16x16x32_bf16 v[102:105], v[172:175], v[196:199], v[102:105]
	v_mfma_f32_16x16x32_bf16 v[98:101], v[180:183], v[196:199], v[98:101]
	v_mfma_f32_16x16x32_bf16 v[86:89], v[172:175], v[204:207], v[86:89]
	v_mfma_f32_16x16x32_bf16 v[82:85], v[180:183], v[204:207], v[82:85]
	v_mfma_f32_16x16x32_bf16 v[70:73], v[172:175], v[212:215], v[70:73]
	v_mfma_f32_16x16x32_bf16 v[66:69], v[180:183], v[212:215], v[66:69]
	v_mfma_f32_16x16x32_bf16 v[118:121], v[176:179], v[192:195], v[118:121]
	v_mfma_f32_16x16x32_bf16 v[114:117], v[184:187], v[192:195], v[114:117]
	v_mfma_f32_16x16x32_bf16 v[102:105], v[176:179], v[200:203], v[102:105]
	v_mfma_f32_16x16x32_bf16 v[98:101], v[184:187], v[200:203], v[98:101]
	v_mfma_f32_16x16x32_bf16 v[86:89], v[176:179], v[208:211], v[86:89]
	v_mfma_f32_16x16x32_bf16 v[82:85], v[184:187], v[208:211], v[82:85]
	v_mfma_f32_16x16x32_bf16 v[70:73], v[176:179], v[216:219], v[70:73]
	v_mfma_f32_16x16x32_bf16 v[66:69], v[184:187], v[216:219], v[66:69]
	s_setprio 0
	s_barrier
; #define PG8_STAGE(bufoff, gbase, voff) do { _Pragma("unroll") for (int _i = 0; _i < 2; ++_i) \
;         __builtin_amdgcn_global_load_lds((const unsigned*)((const char*)(gbase) + (voff)[_i]), (PG8_LAS unsigned*)(lds + (bufoff) + ldsw + _i * 8192), 16, 0, 0); } while (0)
; #define PG8_LDA(dst, b, h) do { _Pragma("unroll") for (int m = 0; m < 4; ++m) _Pragma("unroll") for (int k = 0; k < 2; ++k) dst[m][k] = *(const PG8_LAS bf16x8*)(lds + PG8_SA(b, h) + aoff + m * 2048 + k * 1024); } while (0)
; #define PG8_MMA(ai, bj, At, Bt) do { __builtin_amdgcn_s_setprio(1); _Pragma("unroll") for (int m = 0; m < 4; ++m) _Pragma("unroll") for (int n = 0; n < 2; ++n) _Pragma("unroll") for (int k = 0; k < 2; ++k) \
;         acc[ai][bj][m][n] = __builtin_amdgcn_mfma_f32_16x16x32_bf16(Bt[n][k], At[m][k], acc[ai][bj][m][n], 0, 0, 0); __builtin_amdgcn_s_setprio(0); } while (0)
; #define PG8_WAIT_V(n) asm volatile("s_waitcnt vmcnt(" #n ")" ::: "memory")
; #define PG8_WAIT_L(n) asm volatile("s_waitcnt lgkmcnt(" #n ")" ::: "memory")
; #define PG8_BAR __builtin_amdgcn_s_barrier()
; #define PG8_SCHED __builtin_amdgcn_sched_barrier(0)
; template <class Epi, class Sched, bool ALIGN_EPI = false, bool SP2 = false>
; __device__ __forceinline__ void gemm_phase(PG8_LAS unsigned char* lds, const Gemm g, const Sched& S, const Epi& E) {
;     ...
;             PG8_LDA(At, 1, 1); PG8_STAGE(PG8_SB(1, 0), b3, voffB); PG8_STAGE(PG8_SB(1, 1), b3 + hstep, voffB); PG8_STAGE(PG8_SA(1, 0), a3, voffA);
;             PG8_WAIT_V(8); PG8_WAIT_L(0); PG8_BAR; PG8_MMA(1, 0, At, B0); PG8_MMA(1, 1, At, B1); PG8_BAR; PG8_SCHED;
;     ...
; #pragma unroll
;         for (int a = 0; a < 2; ++a)
; #pragma unroll
;             for (int b = 0; b < 2; ++b)
; #pragma unroll
;                 for (int m = 0; m < 4; ++m)
; #pragma unroll
;                     for (int n = 0; n < 2; ++n) acc[a][b][m][n] = (f32x4){0.f, 0.f, 0.f, 0.f};
;         cur = nxt; cA = nA; cB = nB; ++ui;
	s_add_i32 s3, s3, s31
	v_lshl_add_u64 v[150:151], v[150:151], 0, s[14:15]
	s_mov_b32 m0, s3
	ds_read_b128 v[188:191], v147 offset:49152
	ds_read_b128 v[192:195], v147 offset:50176
	ds_read_b128 v[196:199], v147 offset:51200
	ds_read_b128 v[200:203], v147 offset:52224
	ds_read_b128 v[204:207], v147 offset:53248
	ds_read_b128 v[208:211], v147 offset:54272
	ds_read_b128 v[212:215], v147 offset:55296
	ds_read_b128 v[216:219], v147 offset:56320
	global_load_lds_dwordx4 v[150:151], off
	s_add_i32 m0, s3, 0x2000
	s_add_u32 s48, s48, 0x40080
	v_lshl_add_u64 v[150:151], v[220:221], 0, s[14:15]
	s_addc_u32 s49, s49, 0
	s_add_i32 s3, s60, s31
	global_load_lds_dwordx4 v[150:151], off
	v_lshl_add_u64 v[150:151], s[48:49], 0, v[130:131]
	s_mov_b32 m0, s3
	s_nop 0
	global_load_lds_dwordx4 v[150:151], off
	v_lshl_add_u64 v[150:151], s[48:49], 0, v[132:133]
	s_add_i32 m0, s3, 0x2000
	s_nop 0
	global_load_lds_dwordx4 v[150:151], off
	v_lshl_add_u64 v[150:151], v[222:223], 0, s[14:15]
	s_mov_b32 m0, s56
	s_nop 0
	global_load_lds_dwordx4 v[150:151], off
	v_lshl_add_u64 v[150:151], v[224:225], 0, s[14:15]
	s_mov_b32 m0, s57
	s_nop 0
	global_load_lds_dwordx4 v[150:151], off
	s_waitcnt vmcnt(8)
	s_waitcnt lgkmcnt(0)
	s_barrier
	s_setprio 1
	s_waitcnt lgkmcnt(0)
	v_mfma_f32_16x16x32_bf16 v[62:65], v[154:157], v[188:191], v[62:65]
	s_add_i32 s43, s43, 2
	s_add_u32 s46, s46, 0x100
	s_addc_u32 s47, s47, 0
	s_cmp_gt_u32 s43, 13
	v_mfma_f32_16x16x32_bf16 v[58:61], v[162:165], v[188:191], v[58:61]
	v_mfma_f32_16x16x32_bf16 v[46:49], v[154:157], v[196:199], v[46:49]
	v_mfma_f32_16x16x32_bf16 v[42:45], v[162:165], v[196:199], v[42:45]
	v_mfma_f32_16x16x32_bf16 v[30:33], v[154:157], v[204:207], v[30:33]
	v_mfma_f32_16x16x32_bf16 v[26:29], v[162:165], v[204:207], v[26:29]
	v_mfma_f32_16x16x32_bf16 v[14:17], v[154:157], v[212:215], v[14:17]
	v_mfma_f32_16x16x32_bf16 v[10:13], v[162:165], v[212:215], v[10:13]
	v_mfma_f32_16x16x32_bf16 v[62:65], v[158:161], v[192:195], v[62:65]
	v_mfma_f32_16x16x32_bf16 v[58:61], v[166:169], v[192:195], v[58:61]
	v_mfma_f32_16x16x32_bf16 v[46:49], v[158:161], v[200:203], v[46:49]
	v_mfma_f32_16x16x32_bf16 v[42:45], v[166:169], v[200:203], v[42:45]
	v_mfma_f32_16x16x32_bf16 v[30:33], v[158:161], v[208:211], v[30:33]
	v_mfma_f32_16x16x32_bf16 v[26:29], v[166:169], v[208:211], v[26:29]
	v_mfma_f32_16x16x32_bf16 v[14:17], v[158:161], v[216:219], v[14:17]
	v_mfma_f32_16x16x32_bf16 v[10:13], v[166:169], v[216:219], v[10:13]
	s_setprio 0
	s_setprio 1
	v_mfma_f32_16x16x32_bf16 v[54:57], v[172:175], v[188:191], v[54:57]
	v_mfma_f32_16x16x32_bf16 v[50:53], v[180:183], v[188:191], v[50:53]
	v_mfma_f32_16x16x32_bf16 v[38:41], v[172:175], v[196:199], v[38:41]
	v_mfma_f32_16x16x32_bf16 v[34:37], v[180:183], v[196:199], v[34:37]
	v_mfma_f32_16x16x32_bf16 v[22:25], v[172:175], v[204:207], v[22:25]
	v_mfma_f32_16x16x32_bf16 v[18:21], v[180:183], v[204:207], v[18:21]
	v_mfma_f32_16x16x32_bf16 v[6:9], v[172:175], v[212:215], v[6:9]
	v_mfma_f32_16x16x32_bf16 v[2:5], v[180:183], v[212:215], v[2:5]
	v_mfma_f32_16x16x32_bf16 v[54:57], v[176:179], v[192:195], v[54:57]
	v_mfma_f32_16x16x32_bf16 v[50:53], v[184:187], v[192:195], v[50:53]
	v_mfma_f32_16x16x32_bf16 v[38:41], v[176:179], v[200:203], v[38:41]
	v_mfma_f32_16x16x32_bf16 v[34:37], v[184:187], v[200:203], v[34:37]
	v_mfma_f32_16x16x32_bf16 v[22:25], v[176:179], v[208:211], v[22:25]
	v_mfma_f32_16x16x32_bf16 v[18:21], v[184:187], v[208:211], v[18:21]
	v_mfma_f32_16x16x32_bf16 v[6:9], v[176:179], v[216:219], v[6:9]
	v_mfma_f32_16x16x32_bf16 v[2:5], v[184:187], v[216:219], v[2:5]
	s_setprio 0
	s_barrier
	s_cbranch_scc0 .LBB0_1026
	s_add_u32 s46, s0, 0xffffff00
	s_addc_u32 s47, s1, -1
	s_andn2_b64 vcc, exec, s[6:7]
	s_cbranch_vccnz .LBB0_1029
	v_mov_b32_e32 v2, 0
	s_mov_b32 s30, s36
	s_mov_b32 s28, s38
	s_mov_b64 s[8:9], s[44:45]
	s_mov_b32 s58, s42
	v_mov_b32_e32 v3, v2
	v_mov_b32_e32 v4, v2
	v_mov_b32_e32 v5, v2
	v_mov_b32_e32 v6, v2
	v_mov_b32_e32 v7, v2
	v_mov_b32_e32 v8, v2
	v_mov_b32_e32 v9, v2
	v_mov_b32_e32 v18, v2
	v_mov_b32_e32 v19, v2
	v_mov_b32_e32 v20, v2
	v_mov_b32_e32 v21, v2
	v_mov_b32_e32 v22, v2
	v_mov_b32_e32 v23, v2
	v_mov_b32_e32 v24, v2
	v_mov_b32_e32 v25, v2
	v_mov_b32_e32 v34, v2
	v_mov_b32_e32 v35, v2
	v_mov_b32_e32 v36, v2
	v_mov_b32_e32 v37, v2
	v_mov_b32_e32 v38, v2
	v_mov_b32_e32 v39, v2
	v_mov_b32_e32 v40, v2
	v_mov_b32_e32 v41, v2
	v_mov_b32_e32 v50, v2
	v_mov_b32_e32 v51, v2
	v_mov_b32_e32 v52, v2
	v_mov_b32_e32 v53, v2
	v_mov_b32_e32 v54, v2
	v_mov_b32_e32 v55, v2
	v_mov_b32_e32 v56, v2
	v_mov_b32_e32 v57, v2
	v_mov_b32_e32 v10, v2
	v_mov_b32_e32 v11, v2
	v_mov_b32_e32 v12, v2
	v_mov_b32_e32 v13, v2
	v_mov_b32_e32 v14, v2
	v_mov_b32_e32 v15, v2
	v_mov_b32_e32 v16, v2
	v_mov_b32_e32 v17, v2
	v_mov_b32_e32 v26, v2
	v_mov_b32_e32 v27, v2
	v_mov_b32_e32 v28, v2
	v_mov_b32_e32 v29, v2
	v_mov_b32_e32 v30, v2
	v_mov_b32_e32 v31, v2
	v_mov_b32_e32 v32, v2
	v_mov_b32_e32 v33, v2
	v_mov_b32_e32 v42, v2
	v_mov_b32_e32 v43, v2
	v_mov_b32_e32 v44, v2
	v_mov_b32_e32 v45, v2
	v_mov_b32_e32 v46, v2
	v_mov_b32_e32 v47, v2
	v_mov_b32_e32 v48, v2
	v_mov_b32_e32 v49, v2
	v_mov_b32_e32 v58, v2
	v_mov_b32_e32 v59, v2
	v_mov_b32_e32 v60, v2
	v_mov_b32_e32 v61, v2
	v_mov_b32_e32 v62, v2
	v_mov_b32_e32 v63, v2
	v_mov_b32_e32 v64, v2
	v_mov_b32_e32 v65, v2
	v_mov_b32_e32 v66, v2
	v_mov_b32_e32 v67, v2
	v_mov_b32_e32 v68, v2
	v_mov_b32_e32 v69, v2
	v_mov_b32_e32 v70, v2
	v_mov_b32_e32 v71, v2
	v_mov_b32_e32 v72, v2
	v_mov_b32_e32 v73, v2
	v_mov_b32_e32 v82, v2
	v_mov_b32_e32 v83, v2
	v_mov_b32_e32 v84, v2
	v_mov_b32_e32 v85, v2
	v_mov_b32_e32 v86, v2
	v_mov_b32_e32 v87, v2
	v_mov_b32_e32 v88, v2
	v_mov_b32_e32 v89, v2
	v_mov_b32_e32 v98, v2
	v_mov_b32_e32 v99, v2
	v_mov_b32_e32 v100, v2
	v_mov_b32_e32 v101, v2
	v_mov_b32_e32 v102, v2
	v_mov_b32_e32 v103, v2
	v_mov_b32_e32 v104, v2
	v_mov_b32_e32 v105, v2
	v_mov_b32_e32 v114, v2
	v_mov_b32_e32 v115, v2
	v_mov_b32_e32 v116, v2
	v_mov_b32_e32 v117, v2
	v_mov_b32_e32 v118, v2
	v_mov_b32_e32 v119, v2
	v_mov_b32_e32 v120, v2
	v_mov_b32_e32 v121, v2
	v_mov_b32_e32 v74, v2
	v_mov_b32_e32 v75, v2
	v_mov_b32_e32 v76, v2
	v_mov_b32_e32 v77, v2
	v_mov_b32_e32 v78, v2
	v_mov_b32_e32 v79, v2
	v_mov_b32_e32 v80, v2
	v_mov_b32_e32 v81, v2
	v_mov_b32_e32 v90, v2
	v_mov_b32_e32 v91, v2
	v_mov_b32_e32 v92, v2
	v_mov_b32_e32 v93, v2
	v_mov_b32_e32 v94, v2
	v_mov_b32_e32 v95, v2
	v_mov_b32_e32 v96, v2
	v_mov_b32_e32 v97, v2
	v_mov_b32_e32 v106, v2
	v_mov_b32_e32 v107, v2
	v_mov_b32_e32 v108, v2
	v_mov_b32_e32 v109, v2
	v_mov_b32_e32 v110, v2
	v_mov_b32_e32 v111, v2
	v_mov_b32_e32 v112, v2
	v_mov_b32_e32 v113, v2
	v_mov_b32_e32 v122, v2
	v_mov_b32_e32 v123, v2
	v_mov_b32_e32 v124, v2
	v_mov_b32_e32 v125, v2
	v_mov_b32_e32 v126, v2
	v_mov_b32_e32 v127, v2
	v_mov_b32_e32 v128, v2
	v_mov_b32_e32 v129, v2
	s_andn2_b64 vcc, exec, s[4:5]
	s_cbranch_vccnz .LBB0_1030
	s_branch .LBB0_1031

; #define PG8_STAGE(bufoff, gbase, voff) do { _Pragma("unroll") for (int _i = 0; _i < 2; ++_i) \
;         __builtin_amdgcn_global_load_lds((const unsigned*)((const char*)(gbase) + (voff)[_i]), (PG8_LAS unsigned*)(lds + (bufoff) + ldsw + _i * 8192), 16, 0, 0); } while (0)
; #define PG8_LDA(dst, b, h) do { _Pragma("unroll") for (int m = 0; m < 4; ++m) _Pragma("unroll") for (int k = 0; k < 2; ++k) dst[m][k] = *(const PG8_LAS bf16x8*)(lds + PG8_SA(b, h) + aoff + m * 2048 + k * 1024); } while (0)
; #define PG8_LDB(dst, b, h) do { _Pragma("unroll") for (int n = 0; n < 2; ++n) _Pragma("unroll") for (int k = 0; k < 2; ++k) dst[n][k] = *(const PG8_LAS bf16x8*)(lds + PG8_SB(b, h) + boff + n * 2048 + k * 1024); } while (0)
; #define PG8_MMA(ai, bj, At, Bt) do { __builtin_amdgcn_s_setprio(1); _Pragma("unroll") for (int m = 0; m < 4; ++m) _Pragma("unroll") for (int n = 0; n < 2; ++n) _Pragma("unroll") for (int k = 0; k < 2; ++k) \
;         acc[ai][bj][m][n] = __builtin_amdgcn_mfma_f32_16x16x32_bf16(Bt[n][k], At[m][k], acc[ai][bj][m][n], 0, 0, 0); __builtin_amdgcn_s_setprio(0); } while (0)
; #define PG8_WAIT_V(n) asm volatile("s_waitcnt vmcnt(" #n ")" ::: "memory")
; #define PG8_WAIT_L(n) asm volatile("s_waitcnt lgkmcnt(" #n ")" ::: "memory")
; #define PG8_BAR __builtin_amdgcn_s_barrier()
; #define PG8_SCHED __builtin_amdgcn_sched_barrier(0)
; template <class Epi, class Sched, bool ALIGN_EPI = false, bool SP2 = false>
; __device__ __forceinline__ void gemm_phase(PG8_LAS unsigned char* lds, const Gemm g, const Sched& S, const Epi& E) {
;     ...
;             PG8_LDB(B0, 0, 0); PG8_LDB(B1, 0, 1); PG8_SCHED; PG8_LDA(At, 0, 0); PG8_STAGE(PG8_SA(1, 1), a1 + hstep, voffA);
;             PG8_WAIT_V(8); PG8_WAIT_L(0); PG8_BAR; PG8_MMA(0, 0, At, B0); PG8_MMA(0, 1, At, B1); PG8_BAR; PG8_SCHED;
;             PG8_LDA(At, 0, 1); PG8_STAGE(PG8_SB(0, 0), b2, voffB); PG8_STAGE(PG8_SB(0, 1), b2 + hstep, voffB); PG8_STAGE(PG8_SA(0, 0), a2, voffA);
;             PG8_WAIT_V(8); PG8_WAIT_L(0); PG8_BAR; PG8_MMA(1, 0, At, B0); PG8_MMA(1, 1, At, B1); PG8_BAR; PG8_SCHED;
.LBB0_1175:
	ds_read_b128 v[152:155], v148
	ds_read_b128 v[156:159], v148 offset:1024
	ds_read_b128 v[160:163], v148 offset:2048
	ds_read_b128 v[164:167], v148 offset:3072
	ds_read_b128 v[168:171], v149
	ds_read_b128 v[172:175], v149 offset:1024
	ds_read_b128 v[176:179], v149 offset:2048
	ds_read_b128 v[180:183], v149 offset:3072
	s_add_u32 s3, s40, 0xfffc0080
	s_addc_u32 s42, s41, -1
	s_cmp_eq_u32 s55, 12
	s_cselect_b32 s45, s0, s42
	s_cselect_b32 s44, s1, s3
	s_cselect_b32 s43, s27, s54
	s_cselect_b32 s42, s29, s53
	v_lshl_add_u64 v[216:217], s[40:41], 0, v[138:139]
	s_add_i32 m0, s35, 0xc000
	ds_read_b128 v[184:187], v150
	ds_read_b128 v[188:191], v150 offset:1024
	ds_read_b128 v[192:195], v150 offset:2048
	ds_read_b128 v[196:199], v150 offset:3072
	ds_read_b128 v[200:203], v150 offset:4096
	ds_read_b128 v[204:207], v150 offset:5120
	ds_read_b128 v[208:211], v150 offset:6144
	ds_read_b128 v[212:215], v150 offset:7168
	global_load_lds_dwordx4 v[216:217], off
	v_lshl_add_u64 v[216:217], s[40:41], 0, v[140:141]
	s_add_i32 m0, s35, 0xe000
	s_nop 0
	global_load_lds_dwordx4 v[216:217], off
	s_waitcnt vmcnt(8)
	s_waitcnt lgkmcnt(0)
	s_barrier
	s_setprio 1
	s_waitcnt lgkmcnt(0)
	v_mfma_f32_16x16x32_bf16 v[126:129], v[152:155], v[184:187], v[126:129]
	v_mfma_f32_16x16x32_bf16 v[122:125], v[160:163], v[184:187], v[122:125]
	v_mfma_f32_16x16x32_bf16 v[110:113], v[152:155], v[192:195], v[110:113]
	v_mfma_f32_16x16x32_bf16 v[106:109], v[160:163], v[192:195], v[106:109]
	v_mfma_f32_16x16x32_bf16 v[94:97], v[152:155], v[200:203], v[94:97]
	v_mfma_f32_16x16x32_bf16 v[90:93], v[160:163], v[200:203], v[90:93]
	v_mfma_f32_16x16x32_bf16 v[78:81], v[152:155], v[208:211], v[78:81]
	v_mfma_f32_16x16x32_bf16 v[74:77], v[160:163], v[208:211], v[74:77]
	v_mfma_f32_16x16x32_bf16 v[126:129], v[156:159], v[188:191], v[126:129]
	v_mfma_f32_16x16x32_bf16 v[122:125], v[164:167], v[188:191], v[122:125]
	v_mfma_f32_16x16x32_bf16 v[110:113], v[156:159], v[196:199], v[110:113]
	v_mfma_f32_16x16x32_bf16 v[106:109], v[164:167], v[196:199], v[106:109]
	v_mfma_f32_16x16x32_bf16 v[94:97], v[156:159], v[204:207], v[94:97]
	v_mfma_f32_16x16x32_bf16 v[90:93], v[164:167], v[204:207], v[90:93]
	v_mfma_f32_16x16x32_bf16 v[78:81], v[156:159], v[212:215], v[78:81]
	v_mfma_f32_16x16x32_bf16 v[74:77], v[164:167], v[212:215], v[74:77]
	s_setprio 0
	s_setprio 1
	v_mfma_f32_16x16x32_bf16 v[118:121], v[168:171], v[184:187], v[118:121]
	v_mfma_f32_16x16x32_bf16 v[114:117], v[176:179], v[184:187], v[114:117]
	v_mfma_f32_16x16x32_bf16 v[102:105], v[168:171], v[192:195], v[102:105]
	v_mfma_f32_16x16x32_bf16 v[98:101], v[176:179], v[192:195], v[98:101]
	v_mfma_f32_16x16x32_bf16 v[86:89], v[168:171], v[200:203], v[86:89]
	v_mfma_f32_16x16x32_bf16 v[82:85], v[176:179], v[200:203], v[82:85]
	v_mfma_f32_16x16x32_bf16 v[70:73], v[168:171], v[208:211], v[70:73]
	v_mfma_f32_16x16x32_bf16 v[66:69], v[176:179], v[208:211], v[66:69]
	v_mfma_f32_16x16x32_bf16 v[118:121], v[172:175], v[188:191], v[118:121]
	v_mfma_f32_16x16x32_bf16 v[114:117], v[180:183], v[188:191], v[114:117]
	v_mfma_f32_16x16x32_bf16 v[102:105], v[172:175], v[196:199], v[102:105]
	v_mfma_f32_16x16x32_bf16 v[98:101], v[180:183], v[196:199], v[98:101]
	v_mfma_f32_16x16x32_bf16 v[86:89], v[172:175], v[204:207], v[86:89]
	v_mfma_f32_16x16x32_bf16 v[82:85], v[180:183], v[204:207], v[82:85]
	v_mfma_f32_16x16x32_bf16 v[70:73], v[172:175], v[212:215], v[70:73]
	v_mfma_f32_16x16x32_bf16 v[66:69], v[180:183], v[212:215], v[66:69]
	s_setprio 0
	s_barrier
	s_add_i32 s3, s33, s12
	v_lshl_add_u64 v[216:217], s[42:43], 0, v[134:135]
	s_mov_b32 m0, s3
	ds_read_b128 v[184:187], v150 offset:16384
	ds_read_b128 v[188:191], v150 offset:17408
	ds_read_b128 v[192:195], v150 offset:18432
	ds_read_b128 v[196:199], v150 offset:19456
	ds_read_b128 v[200:203], v150 offset:20480
	ds_read_b128 v[204:207], v150 offset:21504
	ds_read_b128 v[208:211], v150 offset:22528
	ds_read_b128 v[212:215], v150 offset:23552
	global_load_lds_dwordx4 v[216:217], off
	s_add_i32 m0, s3, 0x2000
	s_add_u32 s56, s42, 0x40000
	v_lshl_add_u64 v[218:219], s[42:43], 0, v[130:131]
	s_addc_u32 s57, s43, 0
	s_add_i32 s3, s50, s12
	global_load_lds_dwordx4 v[218:219], off
	v_lshl_add_u64 v[220:221], s[56:57], 0, v[134:135]
	s_mov_b32 m0, s3
	v_lshl_add_u64 v[222:223], s[44:45], 0, v[132:133]
	global_load_lds_dwordx4 v[220:221], off
	v_lshl_add_u64 v[220:221], s[56:57], 0, v[130:131]
	s_add_i32 m0, s3, 0x2000
	s_nop 0
	global_load_lds_dwordx4 v[220:221], off
	v_lshl_add_u64 v[220:221], s[44:45], 0, v[136:137]
	s_mov_b32 m0, s35
	s_nop 0
	global_load_lds_dwordx4 v[220:221], off
	s_mov_b32 m0, s39
	s_nop 0
	global_load_lds_dwordx4 v[222:223], off
	s_waitcnt vmcnt(8)
	s_waitcnt lgkmcnt(0)
	s_barrier
; #define PG8_STAGE(bufoff, gbase, voff) do { _Pragma("unroll") for (int _i = 0; _i < 2; ++_i) \
;         __builtin_amdgcn_global_load_lds((const unsigned*)((const char*)(gbase) + (voff)[_i]), (PG8_LAS unsigned*)(lds + (bufoff) + ldsw + _i * 8192), 16, 0, 0); } while (0)
; #define PG8_LDA(dst, b, h) do { _Pragma("unroll") for (int m = 0; m < 4; ++m) _Pragma("unroll") for (int k = 0; k < 2; ++k) dst[m][k] = *(const PG8_LAS bf16x8*)(lds + PG8_SA(b, h) + aoff + m * 2048 + k * 1024); } while (0)
; #define PG8_LDB(dst, b, h) do { _Pragma("unroll") for (int n = 0; n < 2; ++n) _Pragma("unroll") for (int k = 0; k < 2; ++k) dst[n][k] = *(const PG8_LAS bf16x8*)(lds + PG8_SB(b, h) + boff + n * 2048 + k * 1024); } while (0)
; #define PG8_MMA(ai, bj, At, Bt) do { __builtin_amdgcn_s_setprio(1); _Pragma("unroll") for (int m = 0; m < 4; ++m) _Pragma("unroll") for (int n = 0; n < 2; ++n) _Pragma("unroll") for (int k = 0; k < 2; ++k) \
;         acc[ai][bj][m][n] = __builtin_amdgcn_mfma_f32_16x16x32_bf16(Bt[n][k], At[m][k], acc[ai][bj][m][n], 0, 0, 0); __builtin_amdgcn_s_setprio(0); } while (0)
; #define PG8_WAIT_V(n) asm volatile("s_waitcnt vmcnt(" #n ")" ::: "memory")
; #define PG8_WAIT_L(n) asm volatile("s_waitcnt lgkmcnt(" #n ")" ::: "memory")
; #define PG8_BAR __builtin_amdgcn_s_barrier()
; #define PG8_SCHED __builtin_amdgcn_sched_barrier(0)
; template <class Epi, class Sched, bool ALIGN_EPI = false, bool SP2 = false>
; __device__ __forceinline__ void gemm_phase(PG8_LAS unsigned char* lds, const Gemm g, const Sched& S, const Epi& E) {
;     ...
;             PG8_WAIT_V(8); PG8_WAIT_L(0); PG8_BAR; PG8_MMA(1, 0, At, B0); PG8_MMA(1, 1, At, B1); PG8_BAR; PG8_SCHED;
;             PG8_LDB(B0, 1, 0); PG8_LDB(B1, 1, 1); PG8_SCHED; PG8_LDA(At, 1, 0); PG8_STAGE(PG8_SA(0, 1), a2 + hstep, voffA);
;             PG8_WAIT_V(8); PG8_WAIT_L(0); PG8_BAR; PG8_MMA(0, 0, At, B0); PG8_MMA(0, 1, At, B1); PG8_BAR; PG8_SCHED;
	s_setprio 1
	s_waitcnt lgkmcnt(0)
	v_mfma_f32_16x16x32_bf16 v[62:65], v[152:155], v[184:187], v[62:65]
	v_mfma_f32_16x16x32_bf16 v[58:61], v[160:163], v[184:187], v[58:61]
	v_mfma_f32_16x16x32_bf16 v[46:49], v[152:155], v[192:195], v[46:49]
	v_mfma_f32_16x16x32_bf16 v[42:45], v[160:163], v[192:195], v[42:45]
	v_mfma_f32_16x16x32_bf16 v[30:33], v[152:155], v[200:203], v[30:33]
	v_mfma_f32_16x16x32_bf16 v[26:29], v[160:163], v[200:203], v[26:29]
	v_mfma_f32_16x16x32_bf16 v[14:17], v[152:155], v[208:211], v[14:17]
	v_mfma_f32_16x16x32_bf16 v[10:13], v[160:163], v[208:211], v[10:13]
	v_mfma_f32_16x16x32_bf16 v[62:65], v[156:159], v[188:191], v[62:65]
	v_mfma_f32_16x16x32_bf16 v[58:61], v[164:167], v[188:191], v[58:61]
	v_mfma_f32_16x16x32_bf16 v[46:49], v[156:159], v[196:199], v[46:49]
	v_mfma_f32_16x16x32_bf16 v[42:45], v[164:167], v[196:199], v[42:45]
	v_mfma_f32_16x16x32_bf16 v[30:33], v[156:159], v[204:207], v[30:33]
	v_mfma_f32_16x16x32_bf16 v[26:29], v[164:167], v[204:207], v[26:29]
	v_mfma_f32_16x16x32_bf16 v[14:17], v[156:159], v[212:215], v[14:17]
	v_mfma_f32_16x16x32_bf16 v[10:13], v[164:167], v[212:215], v[10:13]
	s_setprio 0
	s_setprio 1
	v_mfma_f32_16x16x32_bf16 v[54:57], v[168:171], v[184:187], v[54:57]
	v_mfma_f32_16x16x32_bf16 v[50:53], v[176:179], v[184:187], v[50:53]
	v_mfma_f32_16x16x32_bf16 v[38:41], v[168:171], v[192:195], v[38:41]
	v_mfma_f32_16x16x32_bf16 v[34:37], v[176:179], v[192:195], v[34:37]
	v_mfma_f32_16x16x32_bf16 v[22:25], v[168:171], v[200:203], v[22:25]
	v_mfma_f32_16x16x32_bf16 v[18:21], v[176:179], v[200:203], v[18:21]
	v_mfma_f32_16x16x32_bf16 v[6:9], v[168:171], v[208:211], v[6:9]
	v_mfma_f32_16x16x32_bf16 v[2:5], v[176:179], v[208:211], v[2:5]
	v_mfma_f32_16x16x32_bf16 v[54:57], v[172:175], v[188:191], v[54:57]
	v_mfma_f32_16x16x32_bf16 v[50:53], v[180:183], v[188:191], v[50:53]
	v_mfma_f32_16x16x32_bf16 v[38:41], v[172:175], v[196:199], v[38:41]
	v_mfma_f32_16x16x32_bf16 v[34:37], v[180:183], v[196:199], v[34:37]
	v_mfma_f32_16x16x32_bf16 v[22:25], v[172:175], v[204:207], v[22:25]
	v_mfma_f32_16x16x32_bf16 v[18:21], v[180:183], v[204:207], v[18:21]
	v_mfma_f32_16x16x32_bf16 v[6:9], v[172:175], v[212:215], v[6:9]
	v_mfma_f32_16x16x32_bf16 v[2:5], v[180:183], v[212:215], v[2:5]
	s_setprio 0
	s_barrier
	s_add_i32 s3, 0, 0x18000
	v_add_u32_e32 v151, s3, v146
	s_add_i32 s56, 0, 0x1c000
	ds_read_b128 v[152:155], v151
	ds_read_b128 v[156:159], v151 offset:1024
	ds_read_b128 v[160:163], v151 offset:2048
	ds_read_b128 v[164:167], v151 offset:3072
	v_add_u32_e32 v151, s56, v146
	ds_read_b128 v[168:171], v151
	ds_read_b128 v[172:175], v151 offset:1024
	ds_read_b128 v[176:179], v151 offset:2048
	ds_read_b128 v[180:183], v151 offset:3072
	s_add_u32 s44, s44, 0x40000
	s_addc_u32 s45, s45, 0
	s_mov_b32 m0, s46
	v_lshl_add_u64 v[224:225], s[44:45], 0, v[136:137]
	ds_read_b128 v[184:187], v150 offset:32768
	ds_read_b128 v[188:191], v150 offset:33792
	ds_read_b128 v[192:195], v150 offset:34816
	ds_read_b128 v[196:199], v150 offset:35840
	ds_read_b128 v[200:203], v150 offset:36864
	ds_read_b128 v[204:207], v150 offset:37888
	ds_read_b128 v[208:211], v150 offset:38912
	ds_read_b128 v[212:215], v150 offset:39936
	global_load_lds_dwordx4 v[224:225], off
	v_lshl_add_u64 v[224:225], s[44:45], 0, v[132:133]
	s_mov_b32 m0, s47
	s_nop 0
	global_load_lds_dwordx4 v[224:225], off
	s_waitcnt vmcnt(8)
	s_waitcnt lgkmcnt(0)
	s_barrier
	s_setprio 1
	s_waitcnt lgkmcnt(0)
	v_mfma_f32_16x16x32_bf16 v[126:129], v[152:155], v[184:187], v[126:129]
	v_mfma_f32_16x16x32_bf16 v[122:125], v[160:163], v[184:187], v[122:125]
	v_mfma_f32_16x16x32_bf16 v[110:113], v[152:155], v[192:195], v[110:113]
	v_mfma_f32_16x16x32_bf16 v[106:109], v[160:163], v[192:195], v[106:109]
	v_mfma_f32_16x16x32_bf16 v[94:97], v[152:155], v[200:203], v[94:97]
	v_mfma_f32_16x16x32_bf16 v[90:93], v[160:163], v[200:203], v[90:93]
	v_mfma_f32_16x16x32_bf16 v[78:81], v[152:155], v[208:211], v[78:81]
	v_mfma_f32_16x16x32_bf16 v[74:77], v[160:163], v[208:211], v[74:77]
	v_mfma_f32_16x16x32_bf16 v[126:129], v[156:159], v[188:191], v[126:129]
	v_mfma_f32_16x16x32_bf16 v[122:125], v[164:167], v[188:191], v[122:125]
	v_mfma_f32_16x16x32_bf16 v[110:113], v[156:159], v[196:199], v[110:113]
	v_mfma_f32_16x16x32_bf16 v[106:109], v[164:167], v[196:199], v[106:109]
	v_mfma_f32_16x16x32_bf16 v[94:97], v[156:159], v[204:207], v[94:97]
	v_mfma_f32_16x16x32_bf16 v[90:93], v[164:167], v[204:207], v[90:93]
	v_mfma_f32_16x16x32_bf16 v[78:81], v[156:159], v[212:215], v[78:81]
	v_mfma_f32_16x16x32_bf16 v[74:77], v[164:167], v[212:215], v[74:77]
	s_setprio 0
	s_setprio 1
	v_mfma_f32_16x16x32_bf16 v[118:121], v[168:171], v[184:187], v[118:121]
	v_mfma_f32_16x16x32_bf16 v[114:117], v[176:179], v[184:187], v[114:117]
	v_mfma_f32_16x16x32_bf16 v[102:105], v[168:171], v[192:195], v[102:105]
	v_mfma_f32_16x16x32_bf16 v[98:101], v[176:179], v[192:195], v[98:101]
	v_mfma_f32_16x16x32_bf16 v[86:89], v[168:171], v[200:203], v[86:89]
	v_mfma_f32_16x16x32_bf16 v[82:85], v[176:179], v[200:203], v[82:85]
	v_mfma_f32_16x16x32_bf16 v[70:73], v[168:171], v[208:211], v[70:73]
	v_mfma_f32_16x16x32_bf16 v[66:69], v[176:179], v[208:211], v[66:69]
	v_mfma_f32_16x16x32_bf16 v[118:121], v[172:175], v[188:191], v[118:121]
	v_mfma_f32_16x16x32_bf16 v[114:117], v[180:183], v[188:191], v[114:117]
	v_mfma_f32_16x16x32_bf16 v[102:105], v[172:175], v[196:199], v[102:105]
	v_mfma_f32_16x16x32_bf16 v[98:101], v[180:183], v[196:199], v[98:101]
	v_mfma_f32_16x16x32_bf16 v[86:89], v[172:175], v[204:207], v[86:89]
	v_mfma_f32_16x16x32_bf16 v[82:85], v[180:183], v[204:207], v[82:85]
	v_mfma_f32_16x16x32_bf16 v[70:73], v[172:175], v[212:215], v[70:73]
	v_mfma_f32_16x16x32_bf16 v[66:69], v[180:183], v[212:215], v[66:69]
	s_setprio 0
	s_barrier
; #define PG8_STAGE(bufoff, gbase, voff) do { _Pragma("unroll") for (int _i = 0; _i < 2; ++_i) \
;         __builtin_amdgcn_global_load_lds((const unsigned*)((const char*)(gbase) + (voff)[_i]), (PG8_LAS unsigned*)(lds + (bufoff) + ldsw + _i * 8192), 16, 0, 0); } while (0)
; #define PG8_LDA(dst, b, h) do { _Pragma("unroll") for (int m = 0; m < 4; ++m) _Pragma("unroll") for (int k = 0; k < 2; ++k) dst[m][k] = *(const PG8_LAS bf16x8*)(lds + PG8_SA(b, h) + aoff + m * 2048 + k * 1024); } while (0)
; #define PG8_MMA(ai, bj, At, Bt) do { __builtin_amdgcn_s_setprio(1); _Pragma("unroll") for (int m = 0; m < 4; ++m) _Pragma("unroll") for (int n = 0; n < 2; ++n) _Pragma("unroll") for (int k = 0; k < 2; ++k) \
;         acc[ai][bj][m][n] = __builtin_amdgcn_mfma_f32_16x16x32_bf16(Bt[n][k], At[m][k], acc[ai][bj][m][n], 0, 0, 0); __builtin_amdgcn_s_setprio(0); } while (0)
; #define PG8_WAIT_V(n) asm volatile("s_waitcnt vmcnt(" #n ")" ::: "memory")
; #define PG8_WAIT_L(n) asm volatile("s_waitcnt lgkmcnt(" #n ")" ::: "memory")
; #define PG8_BAR __builtin_amdgcn_s_barrier()
; #define PG8_SCHED __builtin_amdgcn_sched_barrier(0)
; template <class Epi, class Sched, bool ALIGN_EPI = false, bool SP2 = false>
; __device__ __forceinline__ void gemm_phase(PG8_LAS unsigned char* lds, const Gemm g, const Sched& S, const Epi& E) {
;     ...
;         for (int t = 0; t < nt; t += 2) {
;             const bool last = (t == nt - 2);
;     ...
;             PG8_LDA(At, 1, 1); PG8_STAGE(PG8_SB(1, 0), b3, voffB); PG8_STAGE(PG8_SB(1, 1), b3 + hstep, voffB); PG8_STAGE(PG8_SA(1, 0), a3, voffA);
;             PG8_WAIT_V(8); PG8_WAIT_L(0); PG8_BAR; PG8_MMA(1, 0, At, B0); PG8_MMA(1, 1, At, B1); PG8_BAR; PG8_SCHED;
	s_add_i32 s3, s3, s12
	v_lshl_add_u64 v[216:217], v[216:217], 0, s[14:15]
	s_mov_b32 m0, s3
	ds_read_b128 v[184:187], v150 offset:49152
	ds_read_b128 v[188:191], v150 offset:50176
	ds_read_b128 v[192:195], v150 offset:51200
	ds_read_b128 v[196:199], v150 offset:52224
	ds_read_b128 v[200:203], v150 offset:53248
	ds_read_b128 v[204:207], v150 offset:54272
	ds_read_b128 v[208:211], v150 offset:55296
	ds_read_b128 v[212:215], v150 offset:56320
	global_load_lds_dwordx4 v[216:217], off
	s_add_i32 m0, s3, 0x2000
	s_add_u32 s42, s42, 0x40080
	v_lshl_add_u64 v[216:217], v[218:219], 0, s[14:15]
	s_addc_u32 s43, s43, 0
	s_add_i32 s3, s56, s12
	global_load_lds_dwordx4 v[216:217], off
	v_lshl_add_u64 v[216:217], s[42:43], 0, v[134:135]
	s_mov_b32 m0, s3
	s_nop 0
	global_load_lds_dwordx4 v[216:217], off
	v_lshl_add_u64 v[216:217], s[42:43], 0, v[130:131]
	s_add_i32 m0, s3, 0x2000
	s_nop 0
	global_load_lds_dwordx4 v[216:217], off
	v_lshl_add_u64 v[216:217], v[220:221], 0, s[14:15]
	s_mov_b32 m0, s48
	s_nop 0
	global_load_lds_dwordx4 v[216:217], off
	v_lshl_add_u64 v[216:217], v[222:223], 0, s[14:15]
	s_mov_b32 m0, s49
	s_nop 0
	global_load_lds_dwordx4 v[216:217], off
	s_waitcnt vmcnt(8)
	s_waitcnt lgkmcnt(0)
	s_barrier
	s_setprio 1
	s_waitcnt lgkmcnt(0)
	v_mfma_f32_16x16x32_bf16 v[62:65], v[152:155], v[184:187], v[62:65]
	s_add_i32 s55, s55, 2
	s_add_u32 s40, s40, 0x100
	s_addc_u32 s41, s41, 0
	s_add_u32 s53, s53, 0x100
	s_addc_u32 s54, s54, 0
	s_cmp_gt_u32 s55, 13
	v_mfma_f32_16x16x32_bf16 v[58:61], v[160:163], v[184:187], v[58:61]
	v_mfma_f32_16x16x32_bf16 v[46:49], v[152:155], v[192:195], v[46:49]
	v_mfma_f32_16x16x32_bf16 v[42:45], v[160:163], v[192:195], v[42:45]
	v_mfma_f32_16x16x32_bf16 v[30:33], v[152:155], v[200:203], v[30:33]
	v_mfma_f32_16x16x32_bf16 v[26:29], v[160:163], v[200:203], v[26:29]
	v_mfma_f32_16x16x32_bf16 v[14:17], v[152:155], v[208:211], v[14:17]
	v_mfma_f32_16x16x32_bf16 v[10:13], v[160:163], v[208:211], v[10:13]
	v_mfma_f32_16x16x32_bf16 v[62:65], v[156:159], v[188:191], v[62:65]
	v_mfma_f32_16x16x32_bf16 v[58:61], v[164:167], v[188:191], v[58:61]
	v_mfma_f32_16x16x32_bf16 v[46:49], v[156:159], v[196:199], v[46:49]
	v_mfma_f32_16x16x32_bf16 v[42:45], v[164:167], v[196:199], v[42:45]
	v_mfma_f32_16x16x32_bf16 v[30:33], v[156:159], v[204:207], v[30:33]
	v_mfma_f32_16x16x32_bf16 v[26:29], v[164:167], v[204:207], v[26:29]
	v_mfma_f32_16x16x32_bf16 v[14:17], v[156:159], v[212:215], v[14:17]
	v_mfma_f32_16x16x32_bf16 v[10:13], v[164:167], v[212:215], v[10:13]
	s_setprio 0
	s_setprio 1
	v_mfma_f32_16x16x32_bf16 v[54:57], v[168:171], v[184:187], v[54:57]
	v_mfma_f32_16x16x32_bf16 v[50:53], v[176:179], v[184:187], v[50:53]
	v_mfma_f32_16x16x32_bf16 v[38:41], v[168:171], v[192:195], v[38:41]
	v_mfma_f32_16x16x32_bf16 v[34:37], v[176:179], v[192:195], v[34:37]
	v_mfma_f32_16x16x32_bf16 v[22:25], v[168:171], v[200:203], v[22:25]
	v_mfma_f32_16x16x32_bf16 v[18:21], v[176:179], v[200:203], v[18:21]
	v_mfma_f32_16x16x32_bf16 v[6:9], v[168:171], v[208:211], v[6:9]
	v_mfma_f32_16x16x32_bf16 v[2:5], v[176:179], v[208:211], v[2:5]
	v_mfma_f32_16x16x32_bf16 v[54:57], v[172:175], v[188:191], v[54:57]
	v_mfma_f32_16x16x32_bf16 v[50:53], v[180:183], v[188:191], v[50:53]
	v_mfma_f32_16x16x32_bf16 v[38:41], v[172:175], v[196:199], v[38:41]
	v_mfma_f32_16x16x32_bf16 v[34:37], v[180:183], v[196:199], v[34:37]
	v_mfma_f32_16x16x32_bf16 v[22:25], v[172:175], v[204:207], v[22:25]
	v_mfma_f32_16x16x32_bf16 v[18:21], v[180:183], v[204:207], v[18:21]
	v_mfma_f32_16x16x32_bf16 v[6:9], v[172:175], v[212:215], v[6:9]
	v_mfma_f32_16x16x32_bf16 v[2:5], v[180:183], v[212:215], v[2:5]
	s_setprio 0
	s_barrier
	s_cbranch_scc0 .LBB0_1175
	s_and_b64 vcc, exec, s[16:17]
	s_cbranch_vccz .LBB0_1178
	s_barrier

; #define PG8_STAGE(bufoff, gbase, voff) do { _Pragma("unroll") for (int _i = 0; _i < 2; ++_i) \
;         __builtin_amdgcn_global_load_lds((const unsigned*)((const char*)(gbase) + (voff)[_i]), (PG8_LAS unsigned*)(lds + (bufoff) + ldsw + _i * 8192), 16, 0, 0); } while (0)
; #define PG8_LDA(dst, b, h) do { _Pragma("unroll") for (int m = 0; m < 4; ++m) _Pragma("unroll") for (int k = 0; k < 2; ++k) dst[m][k] = *(const PG8_LAS bf16x8*)(lds + PG8_SA(b, h) + aoff + m * 2048 + k * 1024); } while (0)
; #define PG8_LDB(dst, b, h) do { _Pragma("unroll") for (int n = 0; n < 2; ++n) _Pragma("unroll") for (int k = 0; k < 2; ++k) dst[n][k] = *(const PG8_LAS bf16x8*)(lds + PG8_SB(b, h) + boff + n * 2048 + k * 1024); } while (0)
; #define PG8_WAIT_V(n) asm volatile("s_waitcnt vmcnt(" #n ")" ::: "memory")
; #define PG8_WAIT_L(n) asm volatile("s_waitcnt lgkmcnt(" #n ")" ::: "memory")
; #define PG8_BAR __builtin_amdgcn_s_barrier()
; #define PG8_SCHED __builtin_amdgcn_sched_barrier(0)
; template <class Epi, class Sched, bool ALIGN_EPI = false, bool SP2 = false>
; __device__ __forceinline__ void gemm_phase(PG8_LAS unsigned char* lds, const Gemm g, const Sched& S, const Epi& E) {
;     ...
;         const char* nA = has_next ? (const char*)g.A + (size_t)nxt.pm * tstep : cA; const char* nB = has_next ? (const char*)g.Bt + (size_t)nxt.pn * tstep : cB;
;         for (int t = 0; t < nt; t += 2) {
;             const bool last = (t == nt - 2);
;             const char* a1 = cA + (size_t)(t + 1) * kstep;
;             const char* a2 = last ? nA : cA + (size_t)(t + 2) * kstep; const char* b2 = last ? nB : cB + (size_t)(t + 2) * kstep;
;             const char* a3 = a2 + kstep; const char* b3 = b2 + kstep;
;             if (last && has_next) S.a_ready(nxt);
;             if constexpr (SP2) {
;             PG8_LDB(B0, 0, 0); PG8_LDB(B1, 0, 1); PG8_SCHED; PG8_LDA(At, 0, 0); PG8_STAGE(PG8_SA(1, 1), a1 + hstep, voffA);
;             PG8_WAIT_V(8); PG8_WAIT_L(0); PG8_BAR; PG8_MMA(0, 0, At, B0); PG8_MMA(0, 1, At, B1); PG8_BAR; PG8_SCHED;
;             PG8_LDA(At, 0, 1); PG8_STAGE(PG8_SB(0, 0), b2, voffB); PG8_STAGE(PG8_SB(0, 1), b2 + hstep, voffB); PG8_STAGE(PG8_SA(0, 0), a2, voffA);
;             PG8_WAIT_V(8); PG8_WAIT_L(0); PG8_BAR; PG8_MMA(1, 0, At, B0); PG8_MMA(1, 1, At, B1); PG8_BAR; PG8_SCHED;
.LBB0_1257:
	v_add_u32_e32 v160, s33, v146
	v_add_u32_e32 v176, s45, v146
	s_add_u32 s26, s14, s24
	ds_read_b128 v[148:151], v160
	ds_read_b128 v[152:155], v160 offset:1024
	ds_read_b128 v[156:159], v160 offset:2048
	ds_read_b128 v[160:163], v160 offset:3072
	ds_read_b128 v[164:167], v176
	ds_read_b128 v[168:171], v176 offset:1024
	ds_read_b128 v[172:175], v176 offset:2048
	ds_read_b128 v[176:179], v176 offset:3072
	s_addc_u32 s27, s15, s25
	s_add_u32 s26, s26, 0x100
	s_addc_u32 s27, s27, 0
	s_add_u32 s50, s21, s24
	s_addc_u32 s51, s48, s25
	s_cmpk_eq_i32 s24, 0x1500
	s_cselect_b32 s29, s23, s27
	s_cselect_b32 s28, s22, s26
	s_cselect_b32 s27, s5, s51
	s_cselect_b32 s26, s4, s50
	v_lshl_add_u64 v[212:213], v[142:143], 0, s[24:25]
	s_add_i32 m0, s37, 0xc000
	ds_read_b128 v[180:183], v147
	ds_read_b128 v[184:187], v147 offset:1024
	ds_read_b128 v[188:191], v147 offset:2048
	ds_read_b128 v[192:195], v147 offset:3072
	ds_read_b128 v[196:199], v147 offset:4096
	ds_read_b128 v[200:203], v147 offset:5120
	ds_read_b128 v[204:207], v147 offset:6144
	ds_read_b128 v[208:211], v147 offset:7168
	global_load_lds_dwordx4 v[212:213], off
	v_lshl_add_u64 v[212:213], v[144:145], 0, s[24:25]
	s_add_i32 m0, s37, 0xe000
	s_nop 0
	global_load_lds_dwordx4 v[212:213], off
	s_waitcnt vmcnt(8)
	s_waitcnt lgkmcnt(0)
	s_barrier
	s_setprio 1
	s_waitcnt lgkmcnt(0)
	v_mfma_f32_16x16x32_bf16 v[126:129], v[148:151], v[180:183], v[126:129]
	v_mfma_f32_16x16x32_bf16 v[122:125], v[156:159], v[180:183], v[122:125]
	v_mfma_f32_16x16x32_bf16 v[114:117], v[148:151], v[188:191], v[114:117]
	v_mfma_f32_16x16x32_bf16 v[106:109], v[156:159], v[188:191], v[106:109]
	v_mfma_f32_16x16x32_bf16 v[98:101], v[148:151], v[196:199], v[98:101]
	v_mfma_f32_16x16x32_bf16 v[90:93], v[156:159], v[196:199], v[90:93]
	v_mfma_f32_16x16x32_bf16 v[82:85], v[148:151], v[204:207], v[82:85]
	v_mfma_f32_16x16x32_bf16 v[74:77], v[156:159], v[204:207], v[74:77]
	v_mfma_f32_16x16x32_bf16 v[126:129], v[152:155], v[184:187], v[126:129]
	v_mfma_f32_16x16x32_bf16 v[122:125], v[160:163], v[184:187], v[122:125]
	v_mfma_f32_16x16x32_bf16 v[114:117], v[152:155], v[192:195], v[114:117]
	v_mfma_f32_16x16x32_bf16 v[106:109], v[160:163], v[192:195], v[106:109]
	v_mfma_f32_16x16x32_bf16 v[98:101], v[152:155], v[200:203], v[98:101]
	v_mfma_f32_16x16x32_bf16 v[90:93], v[160:163], v[200:203], v[90:93]
	v_mfma_f32_16x16x32_bf16 v[82:85], v[152:155], v[208:211], v[82:85]
	v_mfma_f32_16x16x32_bf16 v[74:77], v[160:163], v[208:211], v[74:77]
	s_setprio 0
	s_setprio 1
	v_mfma_f32_16x16x32_bf16 v[118:121], v[164:167], v[180:183], v[118:121]
	v_mfma_f32_16x16x32_bf16 v[110:113], v[172:175], v[180:183], v[110:113]
	v_mfma_f32_16x16x32_bf16 v[102:105], v[164:167], v[188:191], v[102:105]
	v_mfma_f32_16x16x32_bf16 v[94:97], v[172:175], v[188:191], v[94:97]
	v_mfma_f32_16x16x32_bf16 v[86:89], v[164:167], v[196:199], v[86:89]
	v_mfma_f32_16x16x32_bf16 v[78:81], v[172:175], v[196:199], v[78:81]
	v_mfma_f32_16x16x32_bf16 v[70:73], v[164:167], v[204:207], v[70:73]
	v_mfma_f32_16x16x32_bf16 v[66:69], v[172:175], v[204:207], v[66:69]
	v_mfma_f32_16x16x32_bf16 v[118:121], v[168:171], v[184:187], v[118:121]
	v_mfma_f32_16x16x32_bf16 v[110:113], v[176:179], v[184:187], v[110:113]
	v_mfma_f32_16x16x32_bf16 v[102:105], v[168:171], v[192:195], v[102:105]
	v_mfma_f32_16x16x32_bf16 v[94:97], v[176:179], v[192:195], v[94:97]
	v_mfma_f32_16x16x32_bf16 v[86:89], v[168:171], v[200:203], v[86:89]
	v_mfma_f32_16x16x32_bf16 v[78:81], v[176:179], v[200:203], v[78:81]
	v_mfma_f32_16x16x32_bf16 v[70:73], v[168:171], v[208:211], v[70:73]
	v_mfma_f32_16x16x32_bf16 v[66:69], v[176:179], v[208:211], v[66:69]
	s_setprio 0
	s_barrier
	s_add_i32 s50, s33, s36
	v_lshl_add_u64 v[212:213], s[26:27], 0, v[130:131]
	s_mov_b32 m0, s50
	ds_read_b128 v[180:183], v147 offset:16384
	ds_read_b128 v[184:187], v147 offset:17408
	ds_read_b128 v[188:191], v147 offset:18432
	ds_read_b128 v[192:195], v147 offset:19456
	ds_read_b128 v[196:199], v147 offset:20480
	ds_read_b128 v[200:203], v147 offset:21504
	ds_read_b128 v[204:207], v147 offset:22528
	ds_read_b128 v[208:211], v147 offset:23552
	global_load_lds_dwordx4 v[212:213], off
	s_add_i32 m0, s50, 0x2000
	s_add_u32 s50, s26, 0xb0000
	v_lshl_add_u64 v[214:215], s[26:27], 0, v[132:133]
	s_addc_u32 s51, s27, 0
	s_add_i32 s52, s45, s36
	global_load_lds_dwordx4 v[214:215], off
	v_lshl_add_u64 v[216:217], s[50:51], 0, v[130:131]
	s_mov_b32 m0, s52
	v_lshl_add_u64 v[220:221], s[28:29], 0, v[132:133]
	global_load_lds_dwordx4 v[216:217], off
	v_lshl_add_u64 v[216:217], s[50:51], 0, v[132:133]
	s_add_i32 m0, s52, 0x2000
	s_nop 0
	global_load_lds_dwordx4 v[216:217], off
	v_lshl_add_u64 v[216:217], s[28:29], 0, v[130:131]
	s_mov_b32 m0, s37
	s_nop 0
	global_load_lds_dwordx4 v[216:217], off
	s_mov_b32 m0, s39
	s_nop 0
	global_load_lds_dwordx4 v[220:221], off
	s_waitcnt vmcnt(8)
	s_waitcnt lgkmcnt(0)
	s_barrier
; #define PG8_STAGE(bufoff, gbase, voff) do { _Pragma("unroll") for (int _i = 0; _i < 2; ++_i) \
;         __builtin_amdgcn_global_load_lds((const unsigned*)((const char*)(gbase) + (voff)[_i]), (PG8_LAS unsigned*)(lds + (bufoff) + ldsw + _i * 8192), 16, 0, 0); } while (0)
; #define PG8_LDA(dst, b, h) do { _Pragma("unroll") for (int m = 0; m < 4; ++m) _Pragma("unroll") for (int k = 0; k < 2; ++k) dst[m][k] = *(const PG8_LAS bf16x8*)(lds + PG8_SA(b, h) + aoff + m * 2048 + k * 1024); } while (0)
; #define PG8_LDB(dst, b, h) do { _Pragma("unroll") for (int n = 0; n < 2; ++n) _Pragma("unroll") for (int k = 0; k < 2; ++k) dst[n][k] = *(const PG8_LAS bf16x8*)(lds + PG8_SB(b, h) + boff + n * 2048 + k * 1024); } while (0)
; #define PG8_MMA(ai, bj, At, Bt) do { __builtin_amdgcn_s_setprio(1); _Pragma("unroll") for (int m = 0; m < 4; ++m) _Pragma("unroll") for (int n = 0; n < 2; ++n) _Pragma("unroll") for (int k = 0; k < 2; ++k) \
;         acc[ai][bj][m][n] = __builtin_amdgcn_mfma_f32_16x16x32_bf16(Bt[n][k], At[m][k], acc[ai][bj][m][n], 0, 0, 0); __builtin_amdgcn_s_setprio(0); } while (0)
; #define PG8_WAIT_V(n) asm volatile("s_waitcnt vmcnt(" #n ")" ::: "memory")
; #define PG8_WAIT_L(n) asm volatile("s_waitcnt lgkmcnt(" #n ")" ::: "memory")
; #define PG8_BAR __builtin_amdgcn_s_barrier()
; #define PG8_SCHED __builtin_amdgcn_sched_barrier(0)
; template <class Epi, class Sched, bool ALIGN_EPI = false, bool SP2 = false>
; __device__ __forceinline__ void gemm_phase(PG8_LAS unsigned char* lds, const Gemm g, const Sched& S, const Epi& E) {
;     ...
;             PG8_WAIT_V(8); PG8_WAIT_L(0); PG8_BAR; PG8_MMA(1, 0, At, B0); PG8_MMA(1, 1, At, B1); PG8_BAR; PG8_SCHED;
;             PG8_LDB(B0, 1, 0); PG8_LDB(B1, 1, 1); PG8_SCHED; PG8_LDA(At, 1, 0); PG8_STAGE(PG8_SA(0, 1), a2 + hstep, voffA);
;             PG8_WAIT_V(8); PG8_WAIT_L(0); PG8_BAR; PG8_MMA(0, 0, At, B0); PG8_MMA(0, 1, At, B1); PG8_BAR; PG8_SCHED;
	s_setprio 1
	s_waitcnt lgkmcnt(0)
	v_mfma_f32_16x16x32_bf16 v[62:65], v[148:151], v[180:183], v[62:65]
	v_mfma_f32_16x16x32_bf16 v[58:61], v[156:159], v[180:183], v[58:61]
	v_mfma_f32_16x16x32_bf16 v[50:53], v[148:151], v[188:191], v[50:53]
	v_mfma_f32_16x16x32_bf16 v[42:45], v[156:159], v[188:191], v[42:45]
	v_mfma_f32_16x16x32_bf16 v[34:37], v[148:151], v[196:199], v[34:37]
	v_mfma_f32_16x16x32_bf16 v[26:29], v[156:159], v[196:199], v[26:29]
	v_mfma_f32_16x16x32_bf16 v[18:21], v[148:151], v[204:207], v[18:21]
	v_mfma_f32_16x16x32_bf16 v[10:13], v[156:159], v[204:207], v[10:13]
	v_mfma_f32_16x16x32_bf16 v[62:65], v[152:155], v[184:187], v[62:65]
	v_mfma_f32_16x16x32_bf16 v[58:61], v[160:163], v[184:187], v[58:61]
	v_mfma_f32_16x16x32_bf16 v[50:53], v[152:155], v[192:195], v[50:53]
	v_mfma_f32_16x16x32_bf16 v[42:45], v[160:163], v[192:195], v[42:45]
	v_mfma_f32_16x16x32_bf16 v[34:37], v[152:155], v[200:203], v[34:37]
	v_mfma_f32_16x16x32_bf16 v[26:29], v[160:163], v[200:203], v[26:29]
	v_mfma_f32_16x16x32_bf16 v[18:21], v[152:155], v[208:211], v[18:21]
	v_mfma_f32_16x16x32_bf16 v[10:13], v[160:163], v[208:211], v[10:13]
	s_setprio 0
	s_setprio 1
	v_mfma_f32_16x16x32_bf16 v[54:57], v[164:167], v[180:183], v[54:57]
	v_mfma_f32_16x16x32_bf16 v[46:49], v[172:175], v[180:183], v[46:49]
	v_mfma_f32_16x16x32_bf16 v[38:41], v[164:167], v[188:191], v[38:41]
	v_mfma_f32_16x16x32_bf16 v[30:33], v[172:175], v[188:191], v[30:33]
	v_mfma_f32_16x16x32_bf16 v[22:25], v[164:167], v[196:199], v[22:25]
	v_mfma_f32_16x16x32_bf16 v[14:17], v[172:175], v[196:199], v[14:17]
	v_mfma_f32_16x16x32_bf16 v[6:9], v[164:167], v[204:207], v[6:9]
	v_mfma_f32_16x16x32_bf16 v[2:5], v[172:175], v[204:207], v[2:5]
	v_mfma_f32_16x16x32_bf16 v[54:57], v[168:171], v[184:187], v[54:57]
	v_mfma_f32_16x16x32_bf16 v[46:49], v[176:179], v[184:187], v[46:49]
	v_mfma_f32_16x16x32_bf16 v[38:41], v[168:171], v[192:195], v[38:41]
	v_mfma_f32_16x16x32_bf16 v[30:33], v[176:179], v[192:195], v[30:33]
	v_mfma_f32_16x16x32_bf16 v[22:25], v[168:171], v[200:203], v[22:25]
	v_mfma_f32_16x16x32_bf16 v[14:17], v[176:179], v[200:203], v[14:17]
	v_mfma_f32_16x16x32_bf16 v[6:9], v[168:171], v[208:211], v[6:9]
	v_mfma_f32_16x16x32_bf16 v[2:5], v[176:179], v[208:211], v[2:5]
	s_setprio 0
	s_barrier
	s_add_i32 s50, 0, 0x18000
	s_add_i32 s51, 0, 0x1c000
	v_add_u32_e32 v160, s50, v146
	v_add_u32_e32 v176, s51, v146
	ds_read_b128 v[148:151], v160
	ds_read_b128 v[152:155], v160 offset:1024
	ds_read_b128 v[156:159], v160 offset:2048
	ds_read_b128 v[160:163], v160 offset:3072
	ds_read_b128 v[164:167], v176
	ds_read_b128 v[168:171], v176 offset:1024
	ds_read_b128 v[172:175], v176 offset:2048
	ds_read_b128 v[176:179], v176 offset:3072
	s_add_u32 s28, s28, 0xb0000
	s_addc_u32 s29, s29, 0
	s_mov_b32 m0, s40
	v_lshl_add_u64 v[222:223], s[28:29], 0, v[130:131]
	ds_read_b128 v[180:183], v147 offset:32768
	ds_read_b128 v[184:187], v147 offset:33792
	ds_read_b128 v[188:191], v147 offset:34816
	ds_read_b128 v[192:195], v147 offset:35840
	ds_read_b128 v[196:199], v147 offset:36864
	ds_read_b128 v[200:203], v147 offset:37888
	ds_read_b128 v[204:207], v147 offset:38912
	ds_read_b128 v[208:211], v147 offset:39936
	global_load_lds_dwordx4 v[222:223], off
	v_lshl_add_u64 v[222:223], s[28:29], 0, v[132:133]
	s_mov_b32 m0, s41
	s_nop 0
	global_load_lds_dwordx4 v[222:223], off
	s_waitcnt vmcnt(8)
	s_waitcnt lgkmcnt(0)
	s_barrier
	s_setprio 1
	s_waitcnt lgkmcnt(0)
	v_mfma_f32_16x16x32_bf16 v[126:129], v[148:151], v[180:183], v[126:129]
	v_mfma_f32_16x16x32_bf16 v[122:125], v[156:159], v[180:183], v[122:125]
	v_mfma_f32_16x16x32_bf16 v[114:117], v[148:151], v[188:191], v[114:117]
	v_mfma_f32_16x16x32_bf16 v[106:109], v[156:159], v[188:191], v[106:109]
	v_mfma_f32_16x16x32_bf16 v[98:101], v[148:151], v[196:199], v[98:101]
	v_mfma_f32_16x16x32_bf16 v[90:93], v[156:159], v[196:199], v[90:93]
	v_mfma_f32_16x16x32_bf16 v[82:85], v[148:151], v[204:207], v[82:85]
	v_mfma_f32_16x16x32_bf16 v[74:77], v[156:159], v[204:207], v[74:77]
	v_mfma_f32_16x16x32_bf16 v[126:129], v[152:155], v[184:187], v[126:129]
	v_mfma_f32_16x16x32_bf16 v[122:125], v[160:163], v[184:187], v[122:125]
	v_mfma_f32_16x16x32_bf16 v[114:117], v[152:155], v[192:195], v[114:117]
	v_mfma_f32_16x16x32_bf16 v[106:109], v[160:163], v[192:195], v[106:109]
	v_mfma_f32_16x16x32_bf16 v[98:101], v[152:155], v[200:203], v[98:101]
	v_mfma_f32_16x16x32_bf16 v[90:93], v[160:163], v[200:203], v[90:93]
	v_mfma_f32_16x16x32_bf16 v[82:85], v[152:155], v[208:211], v[82:85]
	v_mfma_f32_16x16x32_bf16 v[74:77], v[160:163], v[208:211], v[74:77]
	s_setprio 0
	s_setprio 1
	v_mfma_f32_16x16x32_bf16 v[118:121], v[164:167], v[180:183], v[118:121]
	v_mfma_f32_16x16x32_bf16 v[110:113], v[172:175], v[180:183], v[110:113]
	v_mfma_f32_16x16x32_bf16 v[102:105], v[164:167], v[188:191], v[102:105]
	v_mfma_f32_16x16x32_bf16 v[94:97], v[172:175], v[188:191], v[94:97]
	v_mfma_f32_16x16x32_bf16 v[86:89], v[164:167], v[196:199], v[86:89]
	v_mfma_f32_16x16x32_bf16 v[78:81], v[172:175], v[196:199], v[78:81]
	v_mfma_f32_16x16x32_bf16 v[70:73], v[164:167], v[204:207], v[70:73]
	v_mfma_f32_16x16x32_bf16 v[66:69], v[172:175], v[204:207], v[66:69]
	v_mfma_f32_16x16x32_bf16 v[118:121], v[168:171], v[184:187], v[118:121]
	v_mfma_f32_16x16x32_bf16 v[110:113], v[176:179], v[184:187], v[110:113]
	v_mfma_f32_16x16x32_bf16 v[102:105], v[168:171], v[192:195], v[102:105]
	v_mfma_f32_16x16x32_bf16 v[94:97], v[176:179], v[192:195], v[94:97]
	v_mfma_f32_16x16x32_bf16 v[86:89], v[168:171], v[200:203], v[86:89]
	v_mfma_f32_16x16x32_bf16 v[78:81], v[176:179], v[200:203], v[78:81]
	v_mfma_f32_16x16x32_bf16 v[70:73], v[168:171], v[208:211], v[70:73]
	v_mfma_f32_16x16x32_bf16 v[66:69], v[176:179], v[208:211], v[66:69]
	s_setprio 0
	s_barrier
; #define PG8_STAGE(bufoff, gbase, voff) do { _Pragma("unroll") for (int _i = 0; _i < 2; ++_i) \
;         __builtin_amdgcn_global_load_lds((const unsigned*)((const char*)(gbase) + (voff)[_i]), (PG8_LAS unsigned*)(lds + (bufoff) + ldsw + _i * 8192), 16, 0, 0); } while (0)
; #define PG8_LDA(dst, b, h) do { _Pragma("unroll") for (int m = 0; m < 4; ++m) _Pragma("unroll") for (int k = 0; k < 2; ++k) dst[m][k] = *(const PG8_LAS bf16x8*)(lds + PG8_SA(b, h) + aoff + m * 2048 + k * 1024); } while (0)
; #define PG8_MMA(ai, bj, At, Bt) do { __builtin_amdgcn_s_setprio(1); _Pragma("unroll") for (int m = 0; m < 4; ++m) _Pragma("unroll") for (int n = 0; n < 2; ++n) _Pragma("unroll") for (int k = 0; k < 2; ++k) \
;         acc[ai][bj][m][n] = __builtin_amdgcn_mfma_f32_16x16x32_bf16(Bt[n][k], At[m][k], acc[ai][bj][m][n], 0, 0, 0); __builtin_amdgcn_s_setprio(0); } while (0)
; #define PG8_WAIT_V(n) asm volatile("s_waitcnt vmcnt(" #n ")" ::: "memory")
; #define PG8_WAIT_L(n) asm volatile("s_waitcnt lgkmcnt(" #n ")" ::: "memory")
; #define PG8_BAR __builtin_amdgcn_s_barrier()
; #define PG8_SCHED __builtin_amdgcn_sched_barrier(0)
; template <class Epi, class Sched, bool ALIGN_EPI = false, bool SP2 = false>
; __device__ __forceinline__ void gemm_phase(PG8_LAS unsigned char* lds, const Gemm g, const Sched& S, const Epi& E) {
;     ...
;             PG8_LDA(At, 1, 1); PG8_STAGE(PG8_SB(1, 0), b3, voffB); PG8_STAGE(PG8_SB(1, 1), b3 + hstep, voffB); PG8_STAGE(PG8_SA(1, 0), a3, voffA);
;             PG8_WAIT_V(8); PG8_WAIT_L(0); PG8_BAR; PG8_MMA(1, 0, At, B0); PG8_MMA(1, 1, At, B1); PG8_BAR; PG8_SCHED;
;     ...
;         if (!has_next) break;
; #pragma unroll
;         for (int a = 0; a < 2; ++a)
; #pragma unroll
;             for (int b = 0; b < 2; ++b)
; #pragma unroll
;                 for (int m = 0; m < 4; ++m)
; #pragma unroll
;                     for (int n = 0; n < 2; ++n) acc[a][b][m][n] = (f32x4){0.f, 0.f, 0.f, 0.f};
;         cur = nxt; cA = nA; cB = nB; ++ui;
	s_add_i32 s28, s50, s36
	v_lshl_add_u64 v[212:213], v[212:213], 0, s[16:17]
	s_mov_b32 m0, s28
	ds_read_b128 v[180:183], v147 offset:49152
	ds_read_b128 v[184:187], v147 offset:50176
	ds_read_b128 v[188:191], v147 offset:51200
	ds_read_b128 v[192:195], v147 offset:52224
	ds_read_b128 v[196:199], v147 offset:53248
	ds_read_b128 v[200:203], v147 offset:54272
	ds_read_b128 v[204:207], v147 offset:55296
	ds_read_b128 v[208:211], v147 offset:56320
	global_load_lds_dwordx4 v[212:213], off
	s_add_i32 m0, s28, 0x2000
	s_add_u32 s26, s26, 0xb0080
	v_lshl_add_u64 v[212:213], v[214:215], 0, s[16:17]
	s_addc_u32 s27, s27, 0
	s_add_i32 s28, s51, s36
	global_load_lds_dwordx4 v[212:213], off
	v_lshl_add_u64 v[212:213], s[26:27], 0, v[130:131]
	s_mov_b32 m0, s28
	s_nop 0
	global_load_lds_dwordx4 v[212:213], off
	v_lshl_add_u64 v[212:213], s[26:27], 0, v[132:133]
	s_add_i32 m0, s28, 0x2000
	s_nop 0
	global_load_lds_dwordx4 v[212:213], off
	v_lshl_add_u64 v[212:213], v[216:217], 0, s[16:17]
	s_mov_b32 m0, s42
	s_nop 0
	global_load_lds_dwordx4 v[212:213], off
	v_lshl_add_u64 v[212:213], v[220:221], 0, s[16:17]
	s_mov_b32 m0, s43
	s_nop 0
	global_load_lds_dwordx4 v[212:213], off
	s_waitcnt vmcnt(8)
	s_waitcnt lgkmcnt(0)
	s_barrier
	s_setprio 1
	s_waitcnt lgkmcnt(0)
	v_mfma_f32_16x16x32_bf16 v[62:65], v[148:151], v[180:183], v[62:65]
	s_add_i32 s49, s49, 2
	s_add_u32 s24, s24, 0x100
	s_addc_u32 s25, s25, 0
	s_cmp_gt_u32 s49, 41
	v_mfma_f32_16x16x32_bf16 v[58:61], v[156:159], v[180:183], v[58:61]
	v_mfma_f32_16x16x32_bf16 v[50:53], v[148:151], v[188:191], v[50:53]
	v_mfma_f32_16x16x32_bf16 v[42:45], v[156:159], v[188:191], v[42:45]
	v_mfma_f32_16x16x32_bf16 v[34:37], v[148:151], v[196:199], v[34:37]
	v_mfma_f32_16x16x32_bf16 v[26:29], v[156:159], v[196:199], v[26:29]
	v_mfma_f32_16x16x32_bf16 v[18:21], v[148:151], v[204:207], v[18:21]
	v_mfma_f32_16x16x32_bf16 v[10:13], v[156:159], v[204:207], v[10:13]
	v_mfma_f32_16x16x32_bf16 v[62:65], v[152:155], v[184:187], v[62:65]
	v_mfma_f32_16x16x32_bf16 v[58:61], v[160:163], v[184:187], v[58:61]
	v_mfma_f32_16x16x32_bf16 v[50:53], v[152:155], v[192:195], v[50:53]
	v_mfma_f32_16x16x32_bf16 v[42:45], v[160:163], v[192:195], v[42:45]
	v_mfma_f32_16x16x32_bf16 v[34:37], v[152:155], v[200:203], v[34:37]
	v_mfma_f32_16x16x32_bf16 v[26:29], v[160:163], v[200:203], v[26:29]
	v_mfma_f32_16x16x32_bf16 v[18:21], v[152:155], v[208:211], v[18:21]
	v_mfma_f32_16x16x32_bf16 v[10:13], v[160:163], v[208:211], v[10:13]
	s_setprio 0
	s_setprio 1
	v_mfma_f32_16x16x32_bf16 v[54:57], v[164:167], v[180:183], v[54:57]
	v_mfma_f32_16x16x32_bf16 v[46:49], v[172:175], v[180:183], v[46:49]
	v_mfma_f32_16x16x32_bf16 v[38:41], v[164:167], v[188:191], v[38:41]
	v_mfma_f32_16x16x32_bf16 v[30:33], v[172:175], v[188:191], v[30:33]
	v_mfma_f32_16x16x32_bf16 v[22:25], v[164:167], v[196:199], v[22:25]
	v_mfma_f32_16x16x32_bf16 v[14:17], v[172:175], v[196:199], v[14:17]
	v_mfma_f32_16x16x32_bf16 v[6:9], v[164:167], v[204:207], v[6:9]
	v_mfma_f32_16x16x32_bf16 v[2:5], v[172:175], v[204:207], v[2:5]
	v_mfma_f32_16x16x32_bf16 v[54:57], v[168:171], v[184:187], v[54:57]
	v_mfma_f32_16x16x32_bf16 v[46:49], v[176:179], v[184:187], v[46:49]
	v_mfma_f32_16x16x32_bf16 v[38:41], v[168:171], v[192:195], v[38:41]
	v_mfma_f32_16x16x32_bf16 v[30:33], v[176:179], v[192:195], v[30:33]
	v_mfma_f32_16x16x32_bf16 v[22:25], v[168:171], v[200:203], v[22:25]
	v_mfma_f32_16x16x32_bf16 v[14:17], v[176:179], v[200:203], v[14:17]
	v_mfma_f32_16x16x32_bf16 v[6:9], v[168:171], v[208:211], v[6:9]
	v_mfma_f32_16x16x32_bf16 v[2:5], v[176:179], v[208:211], v[2:5]
	s_setprio 0
	s_barrier
	s_cbranch_scc0 .LBB0_1257
	s_add_u32 s24, s21, 0xffffff00
	s_addc_u32 s25, s48, -1
	s_and_b64 vcc, exec, s[6:7]
	s_cbranch_vccnz .LBB0_1260
	v_mov_b32_e32 v2, 0
	s_mov_b32 s12, s46
	s_mov_b32 s31, s47
	s_mov_b64 s[14:15], s[22:23]
	s_mov_b32 s44, s20
	v_mov_b32_e32 v3, v2
	v_mov_b32_e32 v4, v2
	v_mov_b32_e32 v5, v2
	v_mov_b32_e32 v6, v2
	v_mov_b32_e32 v7, v2
	v_mov_b32_e32 v8, v2
	v_mov_b32_e32 v9, v2
	v_mov_b32_e32 v14, v2
	v_mov_b32_e32 v15, v2
	v_mov_b32_e32 v16, v2
	v_mov_b32_e32 v17, v2
	v_mov_b32_e32 v22, v2
	v_mov_b32_e32 v23, v2
	v_mov_b32_e32 v24, v2
	v_mov_b32_e32 v25, v2
	v_mov_b32_e32 v30, v2
	v_mov_b32_e32 v31, v2
	v_mov_b32_e32 v32, v2
	v_mov_b32_e32 v33, v2
	v_mov_b32_e32 v38, v2
	v_mov_b32_e32 v39, v2
	v_mov_b32_e32 v40, v2
	v_mov_b32_e32 v41, v2
	v_mov_b32_e32 v46, v2
	v_mov_b32_e32 v47, v2
	v_mov_b32_e32 v48, v2
	v_mov_b32_e32 v49, v2
	v_mov_b32_e32 v54, v2
	v_mov_b32_e32 v55, v2
	v_mov_b32_e32 v56, v2
	v_mov_b32_e32 v57, v2
	v_mov_b32_e32 v10, v2
	v_mov_b32_e32 v11, v2
	v_mov_b32_e32 v12, v2
	v_mov_b32_e32 v13, v2
	v_mov_b32_e32 v18, v2
	v_mov_b32_e32 v19, v2
	v_mov_b32_e32 v20, v2
	v_mov_b32_e32 v21, v2
	v_mov_b32_e32 v26, v2
	v_mov_b32_e32 v27, v2
	v_mov_b32_e32 v28, v2
	v_mov_b32_e32 v29, v2
	v_mov_b32_e32 v34, v2
	v_mov_b32_e32 v35, v2
	v_mov_b32_e32 v36, v2
	v_mov_b32_e32 v37, v2
	v_mov_b32_e32 v42, v2
	v_mov_b32_e32 v43, v2
	v_mov_b32_e32 v44, v2
	v_mov_b32_e32 v45, v2
	v_mov_b32_e32 v50, v2
	v_mov_b32_e32 v51, v2
	v_mov_b32_e32 v52, v2
	v_mov_b32_e32 v53, v2
	v_mov_b32_e32 v58, v2
	v_mov_b32_e32 v59, v2
	v_mov_b32_e32 v60, v2
	v_mov_b32_e32 v61, v2
	v_mov_b32_e32 v62, v2
	v_mov_b32_e32 v63, v2
	v_mov_b32_e32 v64, v2
	v_mov_b32_e32 v65, v2
	v_mov_b32_e32 v66, v2
	v_mov_b32_e32 v67, v2
	v_mov_b32_e32 v68, v2
	v_mov_b32_e32 v69, v2
	v_mov_b32_e32 v70, v2
	v_mov_b32_e32 v71, v2
	v_mov_b32_e32 v72, v2
	v_mov_b32_e32 v73, v2
	v_mov_b32_e32 v78, v2
	v_mov_b32_e32 v79, v2
	v_mov_b32_e32 v80, v2
	v_mov_b32_e32 v81, v2
	v_mov_b32_e32 v86, v2
	v_mov_b32_e32 v87, v2
	v_mov_b32_e32 v88, v2
	v_mov_b32_e32 v89, v2
	v_mov_b32_e32 v94, v2
	v_mov_b32_e32 v95, v2
	v_mov_b32_e32 v96, v2
	v_mov_b32_e32 v97, v2
	v_mov_b32_e32 v102, v2
	v_mov_b32_e32 v103, v2
	v_mov_b32_e32 v104, v2
	v_mov_b32_e32 v105, v2
	v_mov_b32_e32 v110, v2
	v_mov_b32_e32 v111, v2
	v_mov_b32_e32 v112, v2
	v_mov_b32_e32 v113, v2
	v_mov_b32_e32 v118, v2
	v_mov_b32_e32 v119, v2
	v_mov_b32_e32 v120, v2
	v_mov_b32_e32 v121, v2
	v_mov_b32_e32 v74, v2
	v_mov_b32_e32 v75, v2
	v_mov_b32_e32 v76, v2
	v_mov_b32_e32 v77, v2
	v_mov_b32_e32 v82, v2
	v_mov_b32_e32 v83, v2
	v_mov_b32_e32 v84, v2
	v_mov_b32_e32 v85, v2
	v_mov_b32_e32 v90, v2
	v_mov_b32_e32 v91, v2
	v_mov_b32_e32 v92, v2
	v_mov_b32_e32 v93, v2
	v_mov_b32_e32 v98, v2
	v_mov_b32_e32 v99, v2
	v_mov_b32_e32 v100, v2
	v_mov_b32_e32 v101, v2
	v_mov_b32_e32 v106, v2
	v_mov_b32_e32 v107, v2
	v_mov_b32_e32 v108, v2
	v_mov_b32_e32 v109, v2
	v_mov_b32_e32 v114, v2
	v_mov_b32_e32 v115, v2
	v_mov_b32_e32 v116, v2
	v_mov_b32_e32 v117, v2
	v_mov_b32_e32 v122, v2
	v_mov_b32_e32 v123, v2
	v_mov_b32_e32 v124, v2
	v_mov_b32_e32 v125, v2
	v_mov_b32_e32 v126, v2
	v_mov_b32_e32 v127, v2
	v_mov_b32_e32 v128, v2
	v_mov_b32_e32 v129, v2
	s_andn2_b64 vcc, exec, s[0:1]
	s_cbranch_vccnz .LBB0_1261
	s_branch .LBB0_1262
